# v GEMM epilogue: the sixteen kv-norm partial-sum loads issued up front with one wait (was four load groups, two of them behind stores)
# speedup vs baseline: 1.0081x; 1.0043x over previous
; #define PG8_STAGE(bufoff, gbase, voff) do { _Pragma("unroll") for (int _i = 0; _i < 2; ++_i) { const char* _gb = (const char*)(gbase) + (size_t)_i * (voff##_q); asm volatile("" : "+s"(_gb)); \
;         __builtin_amdgcn_global_load_lds((const unsigned*)(_gb + (voff)), (LAS unsigned*)(lds + (bufoff) + ldsw + _i * 8192), 16, 0, 0); } } while (0)
; #define PG8_LDA(dst, b, h) do { _Pragma("unroll") for (int m = 0; m < 4; ++m) _Pragma("unroll") for (int k = 0; k < 2; ++k) dst[m][k] = *(const LAS bf16x8*)(lds + PG8_SA(b, h) + aoff + m * 2048 + k * 1024); } while (0)
; #define PG8_LDB(dst, b, h) do { _Pragma("unroll") for (int n = 0; n < 2; ++n) _Pragma("unroll") for (int k = 0; k < 2; ++k) dst[n][k] = *(const LAS bf16x8*)(lds + PG8_SB(b, h) + boff + n * 2048 + k * 1024); } while (0)
; #define PG8_WAIT_V(n) asm volatile("s_waitcnt vmcnt(" #n ")" ::: "memory")
; #define PG8_WAIT_L(n) asm volatile("s_waitcnt lgkmcnt(" #n ")" ::: "memory")
; template <class Epi, class Sched>
; __device__ __forceinline__ void gemm_phase(int wv, LAS unsigned char* lds, const Gemm g, const Sched& S, const Epi& E) { LIDS
;     ...
;         const bool has_next = S.next(ui + 1, nxt);
;         const char* nA = has_next ? (const char*)g.A + (size_t)nxt.pm * g.tstepA : cA; const char* nB = has_next ? (const char*)g.Bt + (size_t)nxt.pn * g.tstepB : cB;
;         for (int t = 0; t < nt; t += 2) {
;             const bool last = (t == nt - 2);
;             const char* a1 = cA + (size_t)(t + 1) * kstepA;
;             const char* a2 = last ? nA : cA + (size_t)(t + 2) * kstepA; const char* b2 = last ? nB : cB + (size_t)(t + 2) * kstepB;
;             const char* a3 = a2 + kstepA; const char* b3 = b2 + kstepB;
;             asm volatile("" : "+s"(a1), "+s"(a2), "+s"(b2), "+s"(a3), "+s"(b3));
;             PG8_LDB(B0, 0, 0); PG8_SCHED; PG8_LDA(At, 0, 0); PG8_STAGE(PG8_SA(1, 1), a1 + hstepA, voffA);
;             PG8_WAIT_L(8); PG8_BAR; PG8_WAIT_L(0); PG8_MMA(0, 0, At, B0); PG8_BAR; PG8_SCHED;
;             PG8_LDB(B1, 0, 1); PG8_STAGE(PG8_SB(0, 0), b2, voffB);
;             PG8_BAR; PG8_WAIT_L(0); PG8_MMA(0, 1, At, B1); PG8_BAR;
;             PG8_LDA(At, 0, 1); PG8_STAGE(PG8_SA(0, 0), a2, voffA);
;             PG8_BAR; PG8_WAIT_L(0); PG8_MMA(1, 0, At, B0); PG8_BAR; PG8_SCHED;
;             PG8_STAGE(PG8_SB(0, 1), b2 + hstepB, voffB);
;             PG8_WAIT_V(6); PG8_BAR; PG8_MMA(1, 1, At, B1); PG8_BAR;
.LBB0_186:
	s_ashr_i32 s13, s12, 31
	s_lshl_b64 s[28:29], s[12:13], 17
	v_readlane_b32 s30, v253, 20
	v_mov_b64_e32 v[4:5], 0x100
	v_readlane_b32 s31, v253, 21
	s_add_u32 s62, s30, s28
	v_cmp_lt_i64_e32 vcc, s[8:9], v[4:5]
	s_addc_u32 s63, s31, s29
	s_and_b64 s[28:29], vcc, exec
	s_cselect_b32 s73, s63, s87
	s_cselect_b32 s72, s62, s86
	s_ashr_i32 s11, s10, 31
	s_lshl_b64 s[28:29], s[10:11], 21
	v_readlane_b32 s11, v253, 16
	s_add_u32 s68, s11, s28
	v_readlane_b32 s11, v253, 17
	s_addc_u32 s69, s11, s29
	s_and_b64 s[28:29], vcc, exec
	s_cselect_b32 s79, s69, s91
	s_cselect_b32 s78, s68, s90
	s_add_u32 s28, s86, 0x80
	s_addc_u32 s29, s87, 0
	s_add_u32 s88, s86, 0x100
	s_addc_u32 s89, s87, 0
	s_add_u32 s94, s90, 0x100
	s_addc_u32 s95, s91, 0
	s_add_u32 s86, s86, 0x180
	s_addc_u32 s87, s87, 0
	s_add_u32 s90, s90, 0x180
	s_addc_u32 s91, s91, 0
	s_add_i32 s13, 16, 0x10000
	s_mov_b64 s[84:85], s[86:87]
	v_add_u32_e32 v174, s13, v156
	ds_read_b128 v[4:7], v174
	ds_read_b128 v[8:11], v174 offset:1024
	ds_read_b128 v[12:15], v174 offset:2048
	ds_read_b128 v[16:19], v174 offset:3072
	s_add_u32 s30, s28, 0x10000
	s_addc_u32 s31, s29, 0
	s_add_i32 s52, s18, 0xc000
	s_add_u32 s28, s28, 0x18000
	ds_read_b128 v[20:23], v157
	ds_read_b128 v[24:27], v157 offset:1024
	ds_read_b128 v[28:31], v157 offset:2048
	ds_read_b128 v[32:35], v157 offset:3072
	ds_read_b128 v[36:39], v157 offset:4096
	ds_read_b128 v[40:43], v157 offset:5120
	ds_read_b128 v[44:47], v157 offset:6144
	ds_read_b128 v[48:51], v157 offset:7168
	s_mov_b32 m0, s52
	v_lshl_add_u64 v[52:53], s[30:31], 0, v[140:141]
	s_addc_u32 s29, s29, 0
	s_add_i32 s11, s18, 0xe000
	global_load_lds_dwordx4 v[52:53], off
	s_mov_b32 m0, s11
	v_lshl_add_u64 v[52:53], s[28:29], 0, v[140:141]
	global_load_lds_dwordx4 v[52:53], off
	s_waitcnt lgkmcnt(8)
	s_barrier
	s_waitcnt lgkmcnt(0)
	s_setprio 1
	s_waitcnt lgkmcnt(0)
	v_mfma_f32_16x16x32_bf16 v[52:55], v[4:7], v[20:23], v[0:3]
	v_mfma_f32_16x16x32_bf16 v[56:59], v[12:15], v[20:23], v[0:3]
	v_mfma_f32_16x16x32_bf16 v[60:63], v[4:7], v[28:31], v[0:3]
	v_mfma_f32_16x16x32_bf16 v[64:67], v[12:15], v[28:31], v[0:3]
	v_mfma_f32_16x16x32_bf16 v[68:71], v[4:7], v[36:39], v[0:3]
	v_mfma_f32_16x16x32_bf16 v[72:75], v[12:15], v[36:39], v[0:3]
	v_mfma_f32_16x16x32_bf16 v[76:79], v[4:7], v[44:47], v[0:3]
	v_mfma_f32_16x16x32_bf16 v[80:83], v[12:15], v[44:47], v[0:3]
	v_mfma_f32_16x16x32_bf16 v[52:55], v[8:11], v[24:27], v[52:55]
	v_mfma_f32_16x16x32_bf16 v[56:59], v[16:19], v[24:27], v[56:59]
	v_mfma_f32_16x16x32_bf16 v[60:63], v[8:11], v[32:35], v[60:63]
	v_mfma_f32_16x16x32_bf16 v[64:67], v[16:19], v[32:35], v[64:67]
	v_mfma_f32_16x16x32_bf16 v[68:71], v[8:11], v[40:43], v[68:71]
	v_mfma_f32_16x16x32_bf16 v[72:75], v[16:19], v[40:43], v[72:75]
	v_mfma_f32_16x16x32_bf16 v[76:79], v[8:11], v[48:51], v[76:79]
	v_mfma_f32_16x16x32_bf16 v[80:83], v[16:19], v[48:51], v[80:83]
	s_setprio 0
	s_barrier
	s_add_i32 s31, 16, 0x14000
	v_add_u32_e32 v175, s31, v156
	s_mov_b64 s[28:29], s[94:95]
	ds_read_b128 v[84:87], v175
	ds_read_b128 v[88:91], v175 offset:1024
	ds_read_b128 v[92:95], v175 offset:2048
	ds_read_b128 v[96:99], v175 offset:3072
	s_add_i32 s30, s13, s17
	v_lshl_add_u64 v[100:101], s[28:29], 0, v[176:177]
	s_add_u32 s28, s94, 0x80000
	s_mov_b32 m0, s30
	s_addc_u32 s29, s95, 0
	s_add_i32 s13, s30, 0x2000
	global_load_lds_dwordx4 v[100:101], off
	s_mov_b32 m0, s13
	v_lshl_add_u64 v[100:101], s[28:29], 0, v[176:177]
	global_load_lds_dwordx4 v[100:101], off
	s_barrier
	s_waitcnt lgkmcnt(0)
	s_setprio 1
	s_waitcnt lgkmcnt(0)
	v_mfma_f32_16x16x32_bf16 v[100:103], v[84:87], v[20:23], v[0:3]
	v_mfma_f32_16x16x32_bf16 v[20:23], v[92:95], v[20:23], v[0:3]
	v_mfma_f32_16x16x32_bf16 v[100:103], v[88:91], v[24:27], v[100:103]
	v_mfma_f32_16x16x32_bf16 v[20:23], v[96:99], v[24:27], v[20:23]
	v_mfma_f32_16x16x32_bf16 v[24:27], v[84:87], v[28:31], v[0:3]
	v_mfma_f32_16x16x32_bf16 v[28:31], v[92:95], v[28:31], v[0:3]
	v_mfma_f32_16x16x32_bf16 v[24:27], v[88:91], v[32:35], v[24:27]
	v_mfma_f32_16x16x32_bf16 v[28:31], v[96:99], v[32:35], v[28:31]
	v_mfma_f32_16x16x32_bf16 v[32:35], v[84:87], v[36:39], v[0:3]
	v_mfma_f32_16x16x32_bf16 v[36:39], v[92:95], v[36:39], v[0:3]
	v_mfma_f32_16x16x32_bf16 v[32:35], v[88:91], v[40:43], v[32:35]
	v_mfma_f32_16x16x32_bf16 v[36:39], v[96:99], v[40:43], v[36:39]
	v_mfma_f32_16x16x32_bf16 v[40:43], v[84:87], v[44:47], v[0:3]
	v_mfma_f32_16x16x32_bf16 v[44:47], v[92:95], v[44:47], v[0:3]
	v_mfma_f32_16x16x32_bf16 v[40:43], v[88:91], v[48:51], v[40:43]
	v_mfma_f32_16x16x32_bf16 v[44:47], v[96:99], v[48:51], v[44:47]
	s_setprio 0
	s_mov_b64 s[28:29], s[88:89]
	s_barrier
	ds_read_b128 v[48:51], v157 offset:16384
	ds_read_b128 v[104:107], v157 offset:17408
	ds_read_b128 v[108:111], v157 offset:18432
	ds_read_b128 v[112:115], v157 offset:19456
	ds_read_b128 v[116:119], v157 offset:20480
	ds_read_b128 v[120:123], v157 offset:21504
	ds_read_b128 v[124:127], v157 offset:22528
	ds_read_b128 v[128:131], v157 offset:23552
	s_mov_b32 m0, s18
	v_lshl_add_u64 v[132:133], s[28:29], 0, v[140:141]
	s_add_u32 s28, s88, 0x8000
	s_addc_u32 s29, s89, 0
	global_load_lds_dwordx4 v[132:133], off
	s_mov_b32 m0, s19
	v_lshl_add_u64 v[132:133], s[28:29], 0, v[140:141]
	global_load_lds_dwordx4 v[132:133], off
	s_barrier
; #define PG8_STAGE(bufoff, gbase, voff) do { _Pragma("unroll") for (int _i = 0; _i < 2; ++_i) { const char* _gb = (const char*)(gbase) + (size_t)_i * (voff##_q); asm volatile("" : "+s"(_gb)); \
;         __builtin_amdgcn_global_load_lds((const unsigned*)(_gb + (voff)), (LAS unsigned*)(lds + (bufoff) + ldsw + _i * 8192), 16, 0, 0); } } while (0)
; #define PG8_LDA(dst, b, h) do { _Pragma("unroll") for (int m = 0; m < 4; ++m) _Pragma("unroll") for (int k = 0; k < 2; ++k) dst[m][k] = *(const LAS bf16x8*)(lds + PG8_SA(b, h) + aoff + m * 2048 + k * 1024); } while (0)
; #define PG8_LDB(dst, b, h) do { _Pragma("unroll") for (int n = 0; n < 2; ++n) _Pragma("unroll") for (int k = 0; k < 2; ++k) dst[n][k] = *(const LAS bf16x8*)(lds + PG8_SB(b, h) + boff + n * 2048 + k * 1024); } while (0)
; #define PG8_MMA(ai, bj, At, Bt) do { __builtin_amdgcn_s_setprio(1); _Pragma("unroll") for (int m = 0; m < 4; ++m) _Pragma("unroll") for (int n = 0; n < 2; ++n) _Pragma("unroll") for (int k = 0; k < 2; ++k) \
;         acc[ai][bj][m][n] = __builtin_amdgcn_mfma_f32_16x16x32_bf16(Bt[n][k], At[m][k], acc[ai][bj][m][n], 0, 0, 0); __builtin_amdgcn_s_setprio(0); } while (0)
; #define PG8_WAIT_V(n) asm volatile("s_waitcnt vmcnt(" #n ")" ::: "memory")
; #define PG8_WAIT_L(n) asm volatile("s_waitcnt lgkmcnt(" #n ")" ::: "memory")
; #define PG8_BAR __builtin_amdgcn_s_barrier()
; #define PG8_SCHED __builtin_amdgcn_sched_barrier(0)
; template <class Epi, class Sched>
; __device__ __forceinline__ void gemm_phase(int wv, LAS unsigned char* lds, const Gemm g, const Sched& S, const Epi& E) { LIDS
;     ...
;             PG8_BAR; PG8_WAIT_L(0); PG8_MMA(0, 1, At, B1); PG8_BAR;
;             PG8_LDA(At, 0, 1); PG8_STAGE(PG8_SA(0, 0), a2, voffA);
;             PG8_BAR; PG8_WAIT_L(0); PG8_MMA(1, 0, At, B0); PG8_BAR; PG8_SCHED;
;             PG8_STAGE(PG8_SB(0, 1), b2 + hstepB, voffB);
;             PG8_WAIT_V(6); PG8_BAR; PG8_MMA(1, 1, At, B1); PG8_BAR;
;             PG8_LDB(B0, 1, 0); PG8_SCHED; PG8_LDA(At, 1, 0); PG8_STAGE(PG8_SA(0, 1), a2 + hstepA, voffA);
;             PG8_WAIT_L(8); PG8_BAR; PG8_WAIT_L(0); PG8_MMA(0, 0, At, B0); PG8_BAR; PG8_SCHED;
;             PG8_LDB(B1, 1, 1); PG8_STAGE(PG8_SB(1, 0), b3, voffB);
	s_waitcnt lgkmcnt(0)
	s_setprio 1
	s_waitcnt lgkmcnt(0)
	v_mfma_f32_16x16x32_bf16 v[132:135], v[4:7], v[48:51], v[0:3]
	v_mfma_f32_16x16x32_bf16 v[142:145], v[4:7], v[108:111], v[0:3]
	v_mfma_f32_16x16x32_bf16 v[150:153], v[4:7], v[116:119], v[0:3]
	v_mfma_f32_16x16x32_bf16 v[4:7], v[4:7], v[124:127], v[0:3]
	v_mfma_f32_16x16x32_bf16 v[132:135], v[8:11], v[104:107], v[132:135]
	v_mfma_f32_16x16x32_bf16 v[136:139], v[12:15], v[48:51], v[0:3]
	v_mfma_f32_16x16x32_bf16 v[142:145], v[8:11], v[112:115], v[142:145]
	v_mfma_f32_16x16x32_bf16 v[146:149], v[12:15], v[108:111], v[0:3]
	v_mfma_f32_16x16x32_bf16 v[150:153], v[8:11], v[120:123], v[150:153]
	v_mfma_f32_16x16x32_bf16 v[158:161], v[12:15], v[116:119], v[0:3]
	v_mfma_f32_16x16x32_bf16 v[4:7], v[8:11], v[128:131], v[4:7]
	v_mfma_f32_16x16x32_bf16 v[8:11], v[12:15], v[124:127], v[0:3]
	v_mfma_f32_16x16x32_bf16 v[136:139], v[16:19], v[104:107], v[136:139]
	v_mfma_f32_16x16x32_bf16 v[146:149], v[16:19], v[112:115], v[146:149]
	v_mfma_f32_16x16x32_bf16 v[158:161], v[16:19], v[120:123], v[158:161]
	v_mfma_f32_16x16x32_bf16 v[8:11], v[16:19], v[128:131], v[8:11]
	s_setprio 0
	s_barrier
	s_add_u32 s28, s94, 0x100000
	s_addc_u32 s29, s95, 0
	s_add_i32 s31, s31, s17
	v_lshl_add_u64 v[12:13], s[28:29], 0, v[176:177]
	s_add_u32 s28, s94, 0x180000
	s_mov_b32 m0, s31
	s_addc_u32 s29, s95, 0
	s_add_i32 s27, s31, 0x2000
	global_load_lds_dwordx4 v[12:13], off
	s_mov_b32 m0, s27
	v_lshl_add_u64 v[12:13], s[28:29], 0, v[176:177]
	global_load_lds_dwordx4 v[12:13], off
	s_waitcnt vmcnt(6)
	s_barrier
	s_setprio 1
	v_mfma_f32_16x16x32_bf16 v[12:15], v[84:87], v[48:51], v[0:3]
	v_mfma_f32_16x16x32_bf16 v[16:19], v[92:95], v[48:51], v[0:3]
	v_mfma_f32_16x16x32_bf16 v[12:15], v[88:91], v[104:107], v[12:15]
	v_mfma_f32_16x16x32_bf16 v[16:19], v[96:99], v[104:107], v[16:19]
	v_mfma_f32_16x16x32_bf16 v[48:51], v[84:87], v[108:111], v[0:3]
	v_mfma_f32_16x16x32_bf16 v[104:107], v[92:95], v[108:111], v[0:3]
	v_mfma_f32_16x16x32_bf16 v[108:111], v[84:87], v[116:119], v[0:3]
	v_mfma_f32_16x16x32_bf16 v[84:87], v[84:87], v[124:127], v[0:3]
	v_mfma_f32_16x16x32_bf16 v[48:51], v[88:91], v[112:115], v[48:51]
	v_mfma_f32_16x16x32_bf16 v[104:107], v[96:99], v[112:115], v[104:107]
	v_mfma_f32_16x16x32_bf16 v[108:111], v[88:91], v[120:123], v[108:111]
	v_mfma_f32_16x16x32_bf16 v[112:115], v[92:95], v[116:119], v[0:3]
	v_mfma_f32_16x16x32_bf16 v[84:87], v[88:91], v[128:131], v[84:87]
	v_mfma_f32_16x16x32_bf16 v[88:91], v[92:95], v[124:127], v[0:3]
	v_mfma_f32_16x16x32_bf16 v[112:115], v[96:99], v[120:123], v[112:115]
	v_mfma_f32_16x16x32_bf16 v[88:91], v[96:99], v[128:131], v[88:91]
	s_setprio 0
	s_add_i32 s55, 16, 0x18000
	v_add_u32_e32 v210, s55, v156
	s_barrier
	ds_read_b128 v[92:95], v210
	ds_read_b128 v[96:99], v210 offset:1024
	ds_read_b128 v[116:119], v210 offset:2048
	ds_read_b128 v[120:123], v210 offset:3072
	s_add_u32 s28, s88, 0x10000
	s_addc_u32 s29, s89, 0
	ds_read_b128 v[124:127], v157 offset:32768
	ds_read_b128 v[128:131], v157 offset:33792
	ds_read_b128 v[162:165], v157 offset:34816
	ds_read_b128 v[166:169], v157 offset:35840
	ds_read_b128 v[170:173], v157 offset:36864
	ds_read_b128 v[178:181], v157 offset:37888
	ds_read_b128 v[182:185], v157 offset:38912
	ds_read_b128 v[186:189], v157 offset:39936
	s_mov_b32 m0, s20
	v_lshl_add_u64 v[154:155], s[28:29], 0, v[140:141]
	s_add_u32 s28, s88, 0x18000
	s_addc_u32 s29, s89, 0
	global_load_lds_dwordx4 v[154:155], off
	s_mov_b32 m0, s21
	v_lshl_add_u64 v[154:155], s[28:29], 0, v[140:141]
	global_load_lds_dwordx4 v[154:155], off
	s_waitcnt lgkmcnt(8)
	s_barrier
	s_waitcnt lgkmcnt(0)
	s_setprio 1
	s_waitcnt lgkmcnt(0)
	v_mfma_f32_16x16x32_bf16 v[52:55], v[92:95], v[124:127], v[52:55]
	v_mfma_f32_16x16x32_bf16 v[56:59], v[116:119], v[124:127], v[56:59]
	v_mfma_f32_16x16x32_bf16 v[60:63], v[92:95], v[162:165], v[60:63]
	v_mfma_f32_16x16x32_bf16 v[64:67], v[116:119], v[162:165], v[64:67]
	v_mfma_f32_16x16x32_bf16 v[68:71], v[92:95], v[170:173], v[68:71]
	v_mfma_f32_16x16x32_bf16 v[72:75], v[116:119], v[170:173], v[72:75]
	v_mfma_f32_16x16x32_bf16 v[76:79], v[92:95], v[182:185], v[76:79]
	v_mfma_f32_16x16x32_bf16 v[80:83], v[116:119], v[182:185], v[80:83]
	v_mfma_f32_16x16x32_bf16 v[52:55], v[96:99], v[128:131], v[52:55]
	v_mfma_f32_16x16x32_bf16 v[56:59], v[120:123], v[128:131], v[56:59]
	v_mfma_f32_16x16x32_bf16 v[60:63], v[96:99], v[166:169], v[60:63]
	v_mfma_f32_16x16x32_bf16 v[64:67], v[120:123], v[166:169], v[64:67]
	v_mfma_f32_16x16x32_bf16 v[68:71], v[96:99], v[178:181], v[68:71]
	v_mfma_f32_16x16x32_bf16 v[72:75], v[120:123], v[178:181], v[72:75]
	v_mfma_f32_16x16x32_bf16 v[76:79], v[96:99], v[186:189], v[76:79]
	v_mfma_f32_16x16x32_bf16 v[80:83], v[120:123], v[186:189], v[80:83]
	s_setprio 0
	s_barrier
	s_add_i32 s58, 16, 0x1c000
	v_add_u32_e32 v211, s58, v156
	s_mov_b64 s[28:29], s[90:91]
	ds_read_b128 v[190:193], v211
	ds_read_b128 v[194:197], v211 offset:1024
	ds_read_b128 v[198:201], v211 offset:2048
	ds_read_b128 v[202:205], v211 offset:3072
	s_add_i32 s55, s55, s17
	v_lshl_add_u64 v[154:155], s[28:29], 0, v[176:177]
	s_add_u32 s28, s90, 0x80000
	s_mov_b32 m0, s55
	s_addc_u32 s29, s91, 0
	global_load_lds_dwordx4 v[154:155], off
	s_nop 0
	v_lshl_add_u64 v[154:155], s[28:29], 0, v[176:177]
	s_add_i32 s28, s55, 0x2000
	s_mov_b32 m0, s28
	s_nop 0
	global_load_lds_dwordx4 v[154:155], off
	s_barrier
; #define PG8_STAGE(bufoff, gbase, voff) do { _Pragma("unroll") for (int _i = 0; _i < 2; ++_i) { const char* _gb = (const char*)(gbase) + (size_t)_i * (voff##_q); asm volatile("" : "+s"(_gb)); \
;         __builtin_amdgcn_global_load_lds((const unsigned*)(_gb + (voff)), (LAS unsigned*)(lds + (bufoff) + ldsw + _i * 8192), 16, 0, 0); } } while (0)
; #define PG8_LDA(dst, b, h) do { _Pragma("unroll") for (int m = 0; m < 4; ++m) _Pragma("unroll") for (int k = 0; k < 2; ++k) dst[m][k] = *(const LAS bf16x8*)(lds + PG8_SA(b, h) + aoff + m * 2048 + k * 1024); } while (0)
; #define PG8_LDB(dst, b, h) do { _Pragma("unroll") for (int n = 0; n < 2; ++n) _Pragma("unroll") for (int k = 0; k < 2; ++k) dst[n][k] = *(const LAS bf16x8*)(lds + PG8_SB(b, h) + boff + n * 2048 + k * 1024); } while (0)
; #define PG8_MMA(ai, bj, At, Bt) do { __builtin_amdgcn_s_setprio(1); _Pragma("unroll") for (int m = 0; m < 4; ++m) _Pragma("unroll") for (int n = 0; n < 2; ++n) _Pragma("unroll") for (int k = 0; k < 2; ++k) \
;         acc[ai][bj][m][n] = __builtin_amdgcn_mfma_f32_16x16x32_bf16(Bt[n][k], At[m][k], acc[ai][bj][m][n], 0, 0, 0); __builtin_amdgcn_s_setprio(0); } while (0)
; #define PG8_WAIT_V(n) asm volatile("s_waitcnt vmcnt(" #n ")" ::: "memory")
; #define PG8_WAIT_L(n) asm volatile("s_waitcnt lgkmcnt(" #n ")" ::: "memory")
; #define PG8_BAR __builtin_amdgcn_s_barrier()
; #define PG8_SCHED __builtin_amdgcn_sched_barrier(0)
; template <class Epi, class Sched>
; __device__ __forceinline__ void gemm_phase(int wv, LAS unsigned char* lds, const Gemm g, const Sched& S, const Epi& E) { LIDS
;     ...
;             PG8_LDB(B0, 0, 0); PG8_SCHED; PG8_LDA(At, 0, 0); PG8_STAGE(PG8_SA(1, 1), a1 + hstepA, voffA);
;             PG8_WAIT_L(8); PG8_BAR; PG8_WAIT_L(0); PG8_MMA(0, 0, At, B0); PG8_BAR; PG8_SCHED;
;             PG8_LDB(B1, 0, 1); PG8_STAGE(PG8_SB(0, 0), b2, voffB);
;     ...
;             PG8_BAR; PG8_WAIT_L(0); PG8_MMA(0, 1, At, B1); PG8_BAR;
;             PG8_LDA(At, 1, 1); PG8_STAGE(PG8_SA(1, 0), a3, voffA);
;             PG8_BAR; PG8_WAIT_L(0); PG8_MMA(1, 0, At, B0); PG8_BAR; PG8_SCHED;
;             PG8_STAGE(PG8_SB(1, 1), b3 + hstepB, voffB);
;             PG8_WAIT_V(6); PG8_BAR; PG8_MMA(1, 1, At, B1); PG8_BAR;
	s_waitcnt lgkmcnt(0)
	s_setprio 1
	s_waitcnt lgkmcnt(0)
	v_mfma_f32_16x16x32_bf16 v[100:103], v[190:193], v[124:127], v[100:103]
	v_mfma_f32_16x16x32_bf16 v[20:23], v[198:201], v[124:127], v[20:23]
	v_mfma_f32_16x16x32_bf16 v[24:27], v[190:193], v[162:165], v[24:27]
	v_mfma_f32_16x16x32_bf16 v[28:31], v[198:201], v[162:165], v[28:31]
	v_mfma_f32_16x16x32_bf16 v[32:35], v[190:193], v[170:173], v[32:35]
	v_mfma_f32_16x16x32_bf16 v[36:39], v[198:201], v[170:173], v[36:39]
	v_mfma_f32_16x16x32_bf16 v[40:43], v[190:193], v[182:185], v[40:43]
	v_mfma_f32_16x16x32_bf16 v[44:47], v[198:201], v[182:185], v[44:47]
	v_mfma_f32_16x16x32_bf16 v[100:103], v[194:197], v[128:131], v[100:103]
	v_mfma_f32_16x16x32_bf16 v[20:23], v[202:205], v[128:131], v[20:23]
	v_mfma_f32_16x16x32_bf16 v[24:27], v[194:197], v[166:169], v[24:27]
	v_mfma_f32_16x16x32_bf16 v[28:31], v[202:205], v[166:169], v[28:31]
	v_mfma_f32_16x16x32_bf16 v[32:35], v[194:197], v[178:181], v[32:35]
	v_mfma_f32_16x16x32_bf16 v[36:39], v[202:205], v[178:181], v[36:39]
	v_mfma_f32_16x16x32_bf16 v[40:43], v[194:197], v[186:189], v[40:43]
	v_mfma_f32_16x16x32_bf16 v[44:47], v[202:205], v[186:189], v[44:47]
	s_setprio 0
	s_mov_b64 s[56:57], s[84:85]
	s_barrier
	ds_read_b128 v[124:127], v157 offset:49152
	ds_read_b128 v[128:131], v157 offset:50176
	ds_read_b128 v[162:165], v157 offset:51200
	ds_read_b128 v[166:169], v157 offset:52224
	ds_read_b128 v[170:173], v157 offset:53248
	ds_read_b128 v[178:181], v157 offset:54272
	ds_read_b128 v[182:185], v157 offset:55296
	ds_read_b128 v[186:189], v157 offset:56320
	s_mov_b32 m0, s24
	v_lshl_add_u64 v[154:155], s[56:57], 0, v[140:141]
	s_add_u32 s56, s84, 0x8000
	s_addc_u32 s57, s85, 0
	global_load_lds_dwordx4 v[154:155], off
	s_mov_b32 m0, s25
	v_lshl_add_u64 v[154:155], s[56:57], 0, v[140:141]
	global_load_lds_dwordx4 v[154:155], off
	s_barrier
	s_waitcnt lgkmcnt(0)
	s_setprio 1
	s_waitcnt lgkmcnt(0)
	v_mfma_f32_16x16x32_bf16 v[132:135], v[92:95], v[124:127], v[132:135]
	v_mfma_f32_16x16x32_bf16 v[136:139], v[116:119], v[124:127], v[136:139]
	v_mfma_f32_16x16x32_bf16 v[142:145], v[92:95], v[162:165], v[142:145]
	v_mfma_f32_16x16x32_bf16 v[146:149], v[116:119], v[162:165], v[146:149]
	v_mfma_f32_16x16x32_bf16 v[150:153], v[92:95], v[170:173], v[150:153]
	v_mfma_f32_16x16x32_bf16 v[158:161], v[116:119], v[170:173], v[158:161]
	v_mfma_f32_16x16x32_bf16 v[4:7], v[92:95], v[182:185], v[4:7]
	v_mfma_f32_16x16x32_bf16 v[8:11], v[116:119], v[182:185], v[8:11]
	v_mfma_f32_16x16x32_bf16 v[132:135], v[96:99], v[128:131], v[132:135]
	v_mfma_f32_16x16x32_bf16 v[136:139], v[120:123], v[128:131], v[136:139]
	v_mfma_f32_16x16x32_bf16 v[142:145], v[96:99], v[166:169], v[142:145]
	v_mfma_f32_16x16x32_bf16 v[146:149], v[120:123], v[166:169], v[146:149]
	v_mfma_f32_16x16x32_bf16 v[150:153], v[96:99], v[178:181], v[150:153]
	v_mfma_f32_16x16x32_bf16 v[158:161], v[120:123], v[178:181], v[158:161]
	v_mfma_f32_16x16x32_bf16 v[4:7], v[96:99], v[186:189], v[4:7]
	v_mfma_f32_16x16x32_bf16 v[8:11], v[120:123], v[186:189], v[8:11]
	s_setprio 0
	s_barrier
	s_add_u32 s56, s90, 0x100000
	s_addc_u32 s57, s91, 0
	s_nop 0
	v_lshl_add_u64 v[92:93], s[56:57], 0, v[176:177]
	s_add_i32 s56, s58, s17
	s_add_u32 s58, s90, 0x180000
	s_mov_b32 m0, s56
	s_addc_u32 s59, s91, 0
	s_add_i32 s29, s56, 0x2000
	global_load_lds_dwordx4 v[92:93], off
	s_mov_b32 m0, s29
	v_lshl_add_u64 v[92:93], s[58:59], 0, v[176:177]
	global_load_lds_dwordx4 v[92:93], off
	s_waitcnt vmcnt(6)
	s_barrier
	s_setprio 1
	v_mfma_f32_16x16x32_bf16 v[12:15], v[190:193], v[124:127], v[12:15]
	v_mfma_f32_16x16x32_bf16 v[16:19], v[198:201], v[124:127], v[16:19]
	v_mfma_f32_16x16x32_bf16 v[48:51], v[190:193], v[162:165], v[48:51]
	v_mfma_f32_16x16x32_bf16 v[92:95], v[198:201], v[162:165], v[104:107]
	v_mfma_f32_16x16x32_bf16 v[96:99], v[190:193], v[170:173], v[108:111]
	v_mfma_f32_16x16x32_bf16 v[104:107], v[198:201], v[170:173], v[112:115]
	v_mfma_f32_16x16x32_bf16 v[84:87], v[190:193], v[182:185], v[84:87]
	v_mfma_f32_16x16x32_bf16 v[88:91], v[198:201], v[182:185], v[88:91]
	v_mfma_f32_16x16x32_bf16 v[12:15], v[194:197], v[128:131], v[12:15]
	v_mfma_f32_16x16x32_bf16 v[16:19], v[202:205], v[128:131], v[16:19]
	v_mfma_f32_16x16x32_bf16 v[48:51], v[194:197], v[166:169], v[48:51]
	v_mfma_f32_16x16x32_bf16 v[92:95], v[202:205], v[166:169], v[92:95]
	v_mfma_f32_16x16x32_bf16 v[96:99], v[194:197], v[178:181], v[96:99]
	v_mfma_f32_16x16x32_bf16 v[104:107], v[202:205], v[178:181], v[104:107]
	v_mfma_f32_16x16x32_bf16 v[84:87], v[194:197], v[186:189], v[84:87]
	v_mfma_f32_16x16x32_bf16 v[88:91], v[202:205], v[186:189], v[88:91]
	s_setprio 0
	s_add_u32 s84, s72, 0x80
	s_addc_u32 s85, s73, 0
	s_add_u32 s90, s78, 0x80
	s_addc_u32 s91, s79, 0
	s_barrier
	ds_read_b128 v[108:111], v174
	ds_read_b128 v[112:115], v174 offset:1024
	ds_read_b128 v[116:119], v174 offset:2048
	ds_read_b128 v[120:123], v174 offset:3072
	s_add_u32 s58, s86, 0x10000
	s_addc_u32 s59, s87, 0
	ds_read_b128 v[124:127], v157
	ds_read_b128 v[128:131], v157 offset:1024
	ds_read_b128 v[162:165], v157 offset:2048
	ds_read_b128 v[166:169], v157 offset:3072
	ds_read_b128 v[170:173], v157 offset:4096
	ds_read_b128 v[178:181], v157 offset:5120
	ds_read_b128 v[182:185], v157 offset:6144
	ds_read_b128 v[186:189], v157 offset:7168
	s_mov_b32 m0, s52
	v_lshl_add_u64 v[154:155], s[58:59], 0, v[140:141]
	s_add_u32 s58, s86, 0x18000
	s_addc_u32 s59, s87, 0
	global_load_lds_dwordx4 v[154:155], off
	s_mov_b32 m0, s11
	v_lshl_add_u64 v[154:155], s[58:59], 0, v[140:141]
	global_load_lds_dwordx4 v[154:155], off
	s_waitcnt lgkmcnt(8)
	s_barrier
; #define PG8_STAGE(bufoff, gbase, voff) do { _Pragma("unroll") for (int _i = 0; _i < 2; ++_i) { const char* _gb = (const char*)(gbase) + (size_t)_i * (voff##_q); asm volatile("" : "+s"(_gb)); \
;         __builtin_amdgcn_global_load_lds((const unsigned*)(_gb + (voff)), (LAS unsigned*)(lds + (bufoff) + ldsw + _i * 8192), 16, 0, 0); } } while (0)
; #define PG8_LDA(dst, b, h) do { _Pragma("unroll") for (int m = 0; m < 4; ++m) _Pragma("unroll") for (int k = 0; k < 2; ++k) dst[m][k] = *(const LAS bf16x8*)(lds + PG8_SA(b, h) + aoff + m * 2048 + k * 1024); } while (0)
; #define PG8_LDB(dst, b, h) do { _Pragma("unroll") for (int n = 0; n < 2; ++n) _Pragma("unroll") for (int k = 0; k < 2; ++k) dst[n][k] = *(const LAS bf16x8*)(lds + PG8_SB(b, h) + boff + n * 2048 + k * 1024); } while (0)
; #define PG8_MMA(ai, bj, At, Bt) do { __builtin_amdgcn_s_setprio(1); _Pragma("unroll") for (int m = 0; m < 4; ++m) _Pragma("unroll") for (int n = 0; n < 2; ++n) _Pragma("unroll") for (int k = 0; k < 2; ++k) \
;         acc[ai][bj][m][n] = __builtin_amdgcn_mfma_f32_16x16x32_bf16(Bt[n][k], At[m][k], acc[ai][bj][m][n], 0, 0, 0); __builtin_amdgcn_s_setprio(0); } while (0)
; #define PG8_WAIT_V(n) asm volatile("s_waitcnt vmcnt(" #n ")" ::: "memory")
; #define PG8_WAIT_L(n) asm volatile("s_waitcnt lgkmcnt(" #n ")" ::: "memory")
; #define PG8_BAR __builtin_amdgcn_s_barrier()
; #define PG8_SCHED __builtin_amdgcn_sched_barrier(0)
; template <class Epi, class Sched>
; __device__ __forceinline__ void gemm_phase(int wv, LAS unsigned char* lds, const Gemm g, const Sched& S, const Epi& E) { LIDS
;     ...
;             PG8_WAIT_L(8); PG8_BAR; PG8_WAIT_L(0); PG8_MMA(0, 0, At, B0); PG8_BAR; PG8_SCHED;
;             PG8_LDB(B1, 0, 1); PG8_STAGE(PG8_SB(0, 0), b2, voffB);
;             PG8_BAR; PG8_WAIT_L(0); PG8_MMA(0, 1, At, B1); PG8_BAR;
;             PG8_LDA(At, 0, 1); PG8_STAGE(PG8_SA(0, 0), a2, voffA);
;             PG8_BAR; PG8_WAIT_L(0); PG8_MMA(1, 0, At, B0); PG8_BAR; PG8_SCHED;
;             PG8_STAGE(PG8_SB(0, 1), b2 + hstepB, voffB);
;             PG8_WAIT_V(6); PG8_BAR; PG8_MMA(1, 1, At, B1); PG8_BAR;
	s_waitcnt lgkmcnt(0)
	s_setprio 1
	s_waitcnt lgkmcnt(0)
	v_mfma_f32_16x16x32_bf16 v[52:55], v[108:111], v[124:127], v[52:55]
	v_mfma_f32_16x16x32_bf16 v[56:59], v[116:119], v[124:127], v[56:59]
	v_mfma_f32_16x16x32_bf16 v[60:63], v[108:111], v[162:165], v[60:63]
	v_mfma_f32_16x16x32_bf16 v[64:67], v[116:119], v[162:165], v[64:67]
	v_mfma_f32_16x16x32_bf16 v[68:71], v[108:111], v[170:173], v[68:71]
	v_mfma_f32_16x16x32_bf16 v[72:75], v[116:119], v[170:173], v[72:75]
	v_mfma_f32_16x16x32_bf16 v[76:79], v[108:111], v[182:185], v[76:79]
	v_mfma_f32_16x16x32_bf16 v[80:83], v[116:119], v[182:185], v[80:83]
	v_mfma_f32_16x16x32_bf16 v[52:55], v[112:115], v[128:131], v[52:55]
	v_mfma_f32_16x16x32_bf16 v[56:59], v[120:123], v[128:131], v[56:59]
	v_mfma_f32_16x16x32_bf16 v[60:63], v[112:115], v[166:169], v[60:63]
	v_mfma_f32_16x16x32_bf16 v[64:67], v[120:123], v[166:169], v[64:67]
	v_mfma_f32_16x16x32_bf16 v[68:71], v[112:115], v[178:181], v[68:71]
	v_mfma_f32_16x16x32_bf16 v[72:75], v[120:123], v[178:181], v[72:75]
	v_mfma_f32_16x16x32_bf16 v[76:79], v[112:115], v[186:189], v[76:79]
	v_mfma_f32_16x16x32_bf16 v[80:83], v[120:123], v[186:189], v[80:83]
	s_setprio 0
	s_barrier
	s_mov_b64 s[58:59], s[78:79]
	ds_read_b128 v[190:193], v175
	ds_read_b128 v[194:197], v175 offset:1024
	ds_read_b128 v[198:201], v175 offset:2048
	ds_read_b128 v[202:205], v175 offset:3072
	s_mov_b32 m0, s30
	v_lshl_add_u64 v[154:155], s[58:59], 0, v[176:177]
	s_add_u32 s58, s78, 0x80000
	s_addc_u32 s59, s79, 0
	global_load_lds_dwordx4 v[154:155], off
	s_mov_b32 m0, s13
	v_lshl_add_u64 v[154:155], s[58:59], 0, v[176:177]
	global_load_lds_dwordx4 v[154:155], off
	s_barrier
	s_waitcnt lgkmcnt(0)
	s_setprio 1
	s_waitcnt lgkmcnt(0)
	v_mfma_f32_16x16x32_bf16 v[100:103], v[190:193], v[124:127], v[100:103]
	v_mfma_f32_16x16x32_bf16 v[20:23], v[198:201], v[124:127], v[20:23]
	v_mfma_f32_16x16x32_bf16 v[24:27], v[190:193], v[162:165], v[24:27]
	v_mfma_f32_16x16x32_bf16 v[28:31], v[198:201], v[162:165], v[28:31]
	v_mfma_f32_16x16x32_bf16 v[32:35], v[190:193], v[170:173], v[32:35]
	v_mfma_f32_16x16x32_bf16 v[36:39], v[198:201], v[170:173], v[36:39]
	v_mfma_f32_16x16x32_bf16 v[40:43], v[190:193], v[182:185], v[40:43]
	v_mfma_f32_16x16x32_bf16 v[44:47], v[198:201], v[182:185], v[44:47]
	v_mfma_f32_16x16x32_bf16 v[206:209], v[194:197], v[128:131], v[100:103]
	v_mfma_f32_16x16x32_bf16 v[20:23], v[202:205], v[128:131], v[20:23]
	v_mfma_f32_16x16x32_bf16 v[24:27], v[194:197], v[166:169], v[24:27]
	v_mfma_f32_16x16x32_bf16 v[28:31], v[202:205], v[166:169], v[28:31]
	v_mfma_f32_16x16x32_bf16 v[32:35], v[194:197], v[178:181], v[32:35]
	v_mfma_f32_16x16x32_bf16 v[36:39], v[202:205], v[178:181], v[36:39]
	v_mfma_f32_16x16x32_bf16 v[40:43], v[194:197], v[186:189], v[40:43]
	v_mfma_f32_16x16x32_bf16 v[162:165], v[202:205], v[186:189], v[44:47]
	s_setprio 0
	s_mov_b64 s[58:59], s[72:73]
	s_barrier
	ds_read_b128 v[44:47], v157 offset:16384
	ds_read_b128 v[100:103], v157 offset:17408
	ds_read_b128 v[124:127], v157 offset:18432
	ds_read_b128 v[128:131], v157 offset:19456
	ds_read_b128 v[166:169], v157 offset:20480
	ds_read_b128 v[170:173], v157 offset:21504
	ds_read_b128 v[178:181], v157 offset:22528
	ds_read_b128 v[182:185], v157 offset:23552
	s_mov_b32 m0, s18
	v_lshl_add_u64 v[154:155], s[58:59], 0, v[140:141]
	s_add_u32 s58, s72, 0x8000
	s_addc_u32 s59, s73, 0
	global_load_lds_dwordx4 v[154:155], off
	s_mov_b32 m0, s19
	v_lshl_add_u64 v[154:155], s[58:59], 0, v[140:141]
	global_load_lds_dwordx4 v[154:155], off
	s_barrier
	s_waitcnt lgkmcnt(0)
	s_setprio 1
	s_waitcnt lgkmcnt(0)
	v_mfma_f32_16x16x32_bf16 v[132:135], v[108:111], v[44:47], v[132:135]
	v_mfma_f32_16x16x32_bf16 v[136:139], v[116:119], v[44:47], v[136:139]
	v_mfma_f32_16x16x32_bf16 v[142:145], v[108:111], v[124:127], v[142:145]
	v_mfma_f32_16x16x32_bf16 v[146:149], v[116:119], v[124:127], v[146:149]
	v_mfma_f32_16x16x32_bf16 v[150:153], v[108:111], v[166:169], v[150:153]
	v_mfma_f32_16x16x32_bf16 v[158:161], v[116:119], v[166:169], v[158:161]
	v_mfma_f32_16x16x32_bf16 v[4:7], v[108:111], v[178:181], v[4:7]
	v_mfma_f32_16x16x32_bf16 v[8:11], v[116:119], v[178:181], v[8:11]
	v_mfma_f32_16x16x32_bf16 v[132:135], v[112:115], v[100:103], v[132:135]
	v_mfma_f32_16x16x32_bf16 v[136:139], v[120:123], v[100:103], v[136:139]
	v_mfma_f32_16x16x32_bf16 v[142:145], v[112:115], v[128:131], v[142:145]
	v_mfma_f32_16x16x32_bf16 v[146:149], v[120:123], v[128:131], v[146:149]
	v_mfma_f32_16x16x32_bf16 v[150:153], v[112:115], v[170:173], v[150:153]
	v_mfma_f32_16x16x32_bf16 v[158:161], v[120:123], v[170:173], v[158:161]
	v_mfma_f32_16x16x32_bf16 v[4:7], v[112:115], v[182:185], v[4:7]
	v_mfma_f32_16x16x32_bf16 v[8:11], v[120:123], v[182:185], v[8:11]
	s_setprio 0
	s_barrier
	s_add_u32 s30, s78, 0x100000
	s_mov_b32 m0, s31
	s_addc_u32 s31, s79, 0
	s_nop 0
	v_lshl_add_u64 v[108:109], s[30:31], 0, v[176:177]
	s_add_u32 s30, s78, 0x180000
	s_addc_u32 s31, s79, 0
	global_load_lds_dwordx4 v[108:109], off
	s_mov_b32 m0, s27
	v_lshl_add_u64 v[108:109], s[30:31], 0, v[176:177]
	global_load_lds_dwordx4 v[108:109], off
	s_waitcnt vmcnt(6)
	s_barrier
; #define PG8_STAGE(bufoff, gbase, voff) do { _Pragma("unroll") for (int _i = 0; _i < 2; ++_i) { const char* _gb = (const char*)(gbase) + (size_t)_i * (voff##_q); asm volatile("" : "+s"(_gb)); \
;         __builtin_amdgcn_global_load_lds((const unsigned*)(_gb + (voff)), (LAS unsigned*)(lds + (bufoff) + ldsw + _i * 8192), 16, 0, 0); } } while (0)
; #define PG8_LDA(dst, b, h) do { _Pragma("unroll") for (int m = 0; m < 4; ++m) _Pragma("unroll") for (int k = 0; k < 2; ++k) dst[m][k] = *(const LAS bf16x8*)(lds + PG8_SA(b, h) + aoff + m * 2048 + k * 1024); } while (0)
; #define PG8_LDB(dst, b, h) do { _Pragma("unroll") for (int n = 0; n < 2; ++n) _Pragma("unroll") for (int k = 0; k < 2; ++k) dst[n][k] = *(const LAS bf16x8*)(lds + PG8_SB(b, h) + boff + n * 2048 + k * 1024); } while (0)
; #define PG8_MMA(ai, bj, At, Bt) do { __builtin_amdgcn_s_setprio(1); _Pragma("unroll") for (int m = 0; m < 4; ++m) _Pragma("unroll") for (int n = 0; n < 2; ++n) _Pragma("unroll") for (int k = 0; k < 2; ++k) \
;         acc[ai][bj][m][n] = __builtin_amdgcn_mfma_f32_16x16x32_bf16(Bt[n][k], At[m][k], acc[ai][bj][m][n], 0, 0, 0); __builtin_amdgcn_s_setprio(0); } while (0)
; #define PG8_WAIT_V(n) asm volatile("s_waitcnt vmcnt(" #n ")" ::: "memory")
; #define PG8_WAIT_L(n) asm volatile("s_waitcnt lgkmcnt(" #n ")" ::: "memory")
; #define PG8_BAR __builtin_amdgcn_s_barrier()
; #define PG8_SCHED __builtin_amdgcn_sched_barrier(0)
; template <class Epi, class Sched>
; __device__ __forceinline__ void gemm_phase(int wv, LAS unsigned char* lds, const Gemm g, const Sched& S, const Epi& E) { LIDS
;     ...
;             PG8_WAIT_V(6); PG8_BAR; PG8_MMA(1, 1, At, B1); PG8_BAR;
;             PG8_LDB(B0, 1, 0); PG8_SCHED; PG8_LDA(At, 1, 0); PG8_STAGE(PG8_SA(0, 1), a2 + hstepA, voffA);
;             PG8_WAIT_L(8); PG8_BAR; PG8_WAIT_L(0); PG8_MMA(0, 0, At, B0); PG8_BAR; PG8_SCHED;
;             PG8_LDB(B1, 1, 1); PG8_STAGE(PG8_SB(1, 0), b3, voffB);
;             PG8_BAR; PG8_WAIT_L(0); PG8_MMA(0, 1, At, B1); PG8_BAR;
;             PG8_LDA(At, 1, 1); PG8_STAGE(PG8_SA(1, 0), a3, voffA);
	s_setprio 1
	v_mfma_f32_16x16x32_bf16 v[12:15], v[190:193], v[44:47], v[12:15]
	v_mfma_f32_16x16x32_bf16 v[186:189], v[194:197], v[100:103], v[12:15]
	v_mfma_f32_16x16x32_bf16 v[12:15], v[198:201], v[44:47], v[16:19]
	v_mfma_f32_16x16x32_bf16 v[218:221], v[202:205], v[100:103], v[12:15]
	v_mfma_f32_16x16x32_bf16 v[12:15], v[190:193], v[124:127], v[48:51]
	v_mfma_f32_16x16x32_bf16 v[222:225], v[194:197], v[128:131], v[12:15]
	v_mfma_f32_16x16x32_bf16 v[12:15], v[198:201], v[124:127], v[92:95]
	v_mfma_f32_16x16x32_bf16 v[226:229], v[202:205], v[128:131], v[12:15]
	v_mfma_f32_16x16x32_bf16 v[12:15], v[190:193], v[166:169], v[96:99]
	v_mfma_f32_16x16x32_bf16 v[230:233], v[194:197], v[170:173], v[12:15]
	v_mfma_f32_16x16x32_bf16 v[12:15], v[198:201], v[166:169], v[104:107]
	v_mfma_f32_16x16x32_bf16 v[166:169], v[202:205], v[170:173], v[12:15]
	v_mfma_f32_16x16x32_bf16 v[12:15], v[190:193], v[178:181], v[84:87]
	v_mfma_f32_16x16x32_bf16 v[170:173], v[194:197], v[182:185], v[12:15]
	v_mfma_f32_16x16x32_bf16 v[12:15], v[198:201], v[178:181], v[88:91]
	v_mfma_f32_16x16x32_bf16 v[178:181], v[202:205], v[182:185], v[12:15]
	s_setprio 0
	s_barrier
	ds_read_b128 v[182:185], v210
	ds_read_b128 v[190:193], v210 offset:1024
	ds_read_b128 v[194:197], v210 offset:2048
	ds_read_b128 v[198:201], v210 offset:3072
	s_add_u32 s30, s72, 0x10000
	s_addc_u32 s31, s73, 0
	ds_read_b128 v[12:15], v157 offset:32768
	ds_read_b128 v[16:19], v157 offset:33792
	ds_read_b128 v[44:47], v157 offset:34816
	ds_read_b128 v[92:95], v157 offset:35840
	ds_read_b128 v[96:99], v157 offset:36864
	ds_read_b128 v[108:111], v157 offset:37888
	ds_read_b128 v[112:115], v157 offset:38912
	ds_read_b128 v[202:205], v157 offset:39936
	s_mov_b32 m0, s20
	v_lshl_add_u64 v[48:49], s[30:31], 0, v[140:141]
	s_add_u32 s30, s72, 0x18000
	s_addc_u32 s31, s73, 0
	global_load_lds_dwordx4 v[48:49], off
	s_mov_b32 m0, s21
	v_lshl_add_u64 v[48:49], s[30:31], 0, v[140:141]
	global_load_lds_dwordx4 v[48:49], off
	s_waitcnt lgkmcnt(8)
	s_barrier
	s_waitcnt lgkmcnt(0)
	s_setprio 1
	s_waitcnt lgkmcnt(0)
	v_mfma_f32_16x16x32_bf16 v[48:51], v[182:185], v[12:15], v[52:55]
	v_mfma_f32_16x16x32_bf16 v[128:131], v[190:193], v[16:19], v[48:51]
	v_mfma_f32_16x16x32_bf16 v[48:51], v[194:197], v[12:15], v[56:59]
	v_mfma_f32_16x16x32_bf16 v[124:127], v[198:201], v[16:19], v[48:51]
	v_mfma_f32_16x16x32_bf16 v[48:51], v[182:185], v[44:47], v[60:63]
	v_mfma_f32_16x16x32_bf16 v[120:123], v[190:193], v[92:95], v[48:51]
	v_mfma_f32_16x16x32_bf16 v[48:51], v[194:197], v[44:47], v[64:67]
	v_mfma_f32_16x16x32_bf16 v[116:119], v[198:201], v[92:95], v[48:51]
	v_mfma_f32_16x16x32_bf16 v[48:51], v[182:185], v[96:99], v[68:71]
	v_mfma_f32_16x16x32_bf16 v[104:107], v[190:193], v[108:111], v[48:51]
	v_mfma_f32_16x16x32_bf16 v[48:51], v[194:197], v[96:99], v[72:75]
	v_mfma_f32_16x16x32_bf16 v[100:103], v[198:201], v[108:111], v[48:51]
	v_mfma_f32_16x16x32_bf16 v[48:51], v[182:185], v[112:115], v[76:79]
	v_mfma_f32_16x16x32_bf16 v[88:91], v[190:193], v[202:205], v[48:51]
	v_mfma_f32_16x16x32_bf16 v[48:51], v[194:197], v[112:115], v[80:83]
	v_mfma_f32_16x16x32_bf16 v[84:87], v[198:201], v[202:205], v[48:51]
	s_setprio 0
	s_barrier
	s_mov_b64 s[30:31], s[90:91]
	ds_read_b128 v[234:237], v211
	ds_read_b128 v[238:241], v211 offset:1024
	ds_read_b128 v[242:245], v211 offset:2048
	ds_read_b128 v[246:249], v211 offset:3072
	s_mov_b32 m0, s55
	v_lshl_add_u64 v[48:49], s[30:31], 0, v[176:177]
	s_add_u32 s30, s90, 0x80000
	s_addc_u32 s31, s91, 0
	global_load_lds_dwordx4 v[48:49], off
	s_mov_b32 m0, s28
	v_lshl_add_u64 v[48:49], s[30:31], 0, v[176:177]
	global_load_lds_dwordx4 v[48:49], off
	s_barrier
	s_waitcnt lgkmcnt(0)
	s_setprio 1
	s_waitcnt lgkmcnt(0)
	v_mfma_f32_16x16x32_bf16 v[48:51], v[234:237], v[12:15], v[206:209]
	v_mfma_f32_16x16x32_bf16 v[12:15], v[242:245], v[12:15], v[20:23]
	v_mfma_f32_16x16x32_bf16 v[60:63], v[246:249], v[16:19], v[12:15]
	v_mfma_f32_16x16x32_bf16 v[12:15], v[234:237], v[44:47], v[24:27]
	v_mfma_f32_16x16x32_bf16 v[64:67], v[238:241], v[16:19], v[48:51]
	v_mfma_f32_16x16x32_bf16 v[48:51], v[238:241], v[92:95], v[12:15]
	v_mfma_f32_16x16x32_bf16 v[12:15], v[242:245], v[44:47], v[28:31]
	v_mfma_f32_16x16x32_bf16 v[44:47], v[246:249], v[92:95], v[12:15]
	v_mfma_f32_16x16x32_bf16 v[12:15], v[234:237], v[96:99], v[32:35]
	v_mfma_f32_16x16x32_bf16 v[32:35], v[238:241], v[108:111], v[12:15]
	v_mfma_f32_16x16x32_bf16 v[12:15], v[242:245], v[96:99], v[36:39]
	v_mfma_f32_16x16x32_bf16 v[28:31], v[246:249], v[108:111], v[12:15]
	v_mfma_f32_16x16x32_bf16 v[12:15], v[234:237], v[112:115], v[40:43]
	v_mfma_f32_16x16x32_bf16 v[16:19], v[238:241], v[202:205], v[12:15]
	v_mfma_f32_16x16x32_bf16 v[12:15], v[242:245], v[112:115], v[162:165]
	v_mfma_f32_16x16x32_bf16 v[12:15], v[246:249], v[202:205], v[12:15]
	s_setprio 0
	s_mov_b64 s[30:31], s[84:85]
	s_barrier
	ds_read_b128 v[20:23], v157 offset:49152
	ds_read_b128 v[24:27], v157 offset:50176
	ds_read_b128 v[36:39], v157 offset:51200
	ds_read_b128 v[162:165], v157 offset:52224
	ds_read_b128 v[202:205], v157 offset:53248
	ds_read_b128 v[206:209], v157 offset:54272
	ds_read_b128 v[210:213], v157 offset:55296
	ds_read_b128 v[40:43], v157 offset:56320
	s_mov_b32 m0, s24
	v_lshl_add_u64 v[52:53], s[30:31], 0, v[140:141]
	s_add_u32 s30, s84, 0x8000
	s_addc_u32 s31, s85, 0
	global_load_lds_dwordx4 v[52:53], off
	s_mov_b32 m0, s25
	v_lshl_add_u64 v[52:53], s[30:31], 0, v[140:141]
	global_load_lds_dwordx4 v[52:53], off
	s_barrier
; __device__ __forceinline__ int lane_id_asm() { int x; asm volatile("v_mbcnt_lo_u32_b32 %0, -1, 0\n\tv_mbcnt_hi_u32_b32 %0, -1, %0" : "=&v"(x)); return x; }
; #define PG8_STAGE(bufoff, gbase, voff) do { _Pragma("unroll") for (int _i = 0; _i < 2; ++_i) { const char* _gb = (const char*)(gbase) + (size_t)_i * (voff##_q); asm volatile("" : "+s"(_gb)); \
;         __builtin_amdgcn_global_load_lds((const unsigned*)(_gb + (voff)), (LAS unsigned*)(lds + (bufoff) + ldsw + _i * 8192), 16, 0, 0); } } while (0)
; #define PG8_MMA(ai, bj, At, Bt) do { __builtin_amdgcn_s_setprio(1); _Pragma("unroll") for (int m = 0; m < 4; ++m) _Pragma("unroll") for (int n = 0; n < 2; ++n) _Pragma("unroll") for (int k = 0; k < 2; ++k) \
;         acc[ai][bj][m][n] = __builtin_amdgcn_mfma_f32_16x16x32_bf16(Bt[n][k], At[m][k], acc[ai][bj][m][n], 0, 0, 0); __builtin_amdgcn_s_setprio(0); } while (0)
; #define PG8_WAIT_V(n) asm volatile("s_waitcnt vmcnt(" #n ")" ::: "memory")
; #define PG8_WAIT_L(n) asm volatile("s_waitcnt lgkmcnt(" #n ")" ::: "memory")
; #define PG8_BAR __builtin_amdgcn_s_barrier()
; #define PG8_SCHED __builtin_amdgcn_sched_barrier(0)
; template <class Epi, class Sched>
; __device__ __forceinline__ void gemm_phase(int wv, LAS unsigned char* lds, const Gemm g, const Sched& S, const Epi& E) { LIDS
;     ...
;             PG8_BAR; PG8_WAIT_L(0); PG8_MMA(1, 0, At, B0); PG8_BAR; PG8_SCHED;
;             PG8_STAGE(PG8_SB(1, 1), b3 + hstepB, voffB);
;             PG8_WAIT_V(6); PG8_BAR; PG8_MMA(1, 1, At, B1); PG8_BAR;
;         }
;         { const int l2 = lane_id_asm(); E(acc, cur, wr, wc, l2 & 15, l2 >> 4); }
;     __device__ __forceinline__ void operator()(const AccT& acc, const Unit& u, int wr, int wc, int fr, int fq) const {
;         EPI_ROWS(u)
; #pragma unroll
;         for (int bj = 0; bj < 2; ++bj) {
;             const int col = colbase + bj * HALF;
;             f32x4 s0, s1;
; #pragma unroll
;             for (int j = 0; j < 4; ++j) { const f32x4 pc = *(const f32x4*)(ssp + (size_t)(col + j) * 16 + 8), pd = *(const f32x4*)(ssp + (size_t)(col + 4 + j) * 16 + 8);
;                 s0[j] = rsqrtf(((pc[0] + pc[1]) + (pc[2] + pc[3])) * (1.0f / 256.0f) + EPS); s1[j] = rsqrtf(((pd[0] + pd[1]) + (pd[2] + pd[3])) * (1.0f / 256.0f) + EPS); }
	s_waitcnt lgkmcnt(0)
	s_setprio 1
	s_waitcnt lgkmcnt(0)
	v_mfma_f32_16x16x32_bf16 v[52:55], v[182:185], v[20:23], v[132:135]
	v_mfma_f32_16x16x32_bf16 v[112:115], v[190:193], v[24:27], v[52:55]
	v_mfma_f32_16x16x32_bf16 v[52:55], v[194:197], v[20:23], v[136:139]
	v_mfma_f32_16x16x32_bf16 v[108:111], v[198:201], v[24:27], v[52:55]
	v_mfma_f32_16x16x32_bf16 v[52:55], v[182:185], v[36:39], v[142:145]
	v_mfma_f32_16x16x32_bf16 v[96:99], v[190:193], v[162:165], v[52:55]
	v_mfma_f32_16x16x32_bf16 v[52:55], v[194:197], v[36:39], v[146:149]
	v_mfma_f32_16x16x32_bf16 v[92:95], v[198:201], v[162:165], v[52:55]
	v_mfma_f32_16x16x32_bf16 v[52:55], v[182:185], v[202:205], v[150:153]
	v_mfma_f32_16x16x32_bf16 v[4:7], v[182:185], v[210:213], v[4:7]
	v_mfma_f32_16x16x32_bf16 v[80:83], v[190:193], v[206:209], v[52:55]
	v_mfma_f32_16x16x32_bf16 v[52:55], v[194:197], v[202:205], v[158:161]
	v_mfma_f32_16x16x32_bf16 v[72:75], v[190:193], v[40:43], v[4:7]
	v_mfma_f32_16x16x32_bf16 v[4:7], v[194:197], v[210:213], v[8:11]
	v_mfma_f32_16x16x32_bf16 v[76:79], v[198:201], v[206:209], v[52:55]
	v_mfma_f32_16x16x32_bf16 v[68:71], v[198:201], v[40:43], v[4:7]
	s_setprio 0
	s_barrier
	s_add_u32 s30, s90, 0x100000
	s_addc_u32 s31, s91, 0
	s_mov_b32 m0, s56
	s_nop 0
	v_lshl_add_u64 v[4:5], s[30:31], 0, v[176:177]
	s_add_u32 s30, s90, 0x180000
	s_addc_u32 s31, s91, 0
	global_load_lds_dwordx4 v[4:5], off
	s_mov_b32 m0, s29
	v_lshl_add_u64 v[4:5], s[30:31], 0, v[176:177]
	global_load_lds_dwordx4 v[4:5], off
	s_waitcnt vmcnt(6)
	s_barrier
	s_setprio 1
	v_mfma_f32_16x16x32_bf16 v[4:7], v[234:237], v[20:23], v[186:189]
	v_mfma_f32_16x16x32_bf16 v[56:59], v[238:241], v[24:27], v[4:7]
	v_mfma_f32_16x16x32_bf16 v[4:7], v[242:245], v[20:23], v[218:221]
	v_mfma_f32_16x16x32_bf16 v[52:55], v[246:249], v[24:27], v[4:7]
	v_mfma_f32_16x16x32_bf16 v[4:7], v[234:237], v[36:39], v[222:225]
	v_mfma_f32_16x16x32_bf16 v[158:161], v[238:241], v[162:165], v[4:7]
	v_mfma_f32_16x16x32_bf16 v[4:7], v[242:245], v[36:39], v[226:229]
	v_mfma_f32_16x16x32_bf16 v[36:39], v[246:249], v[162:165], v[4:7]
	v_mfma_f32_16x16x32_bf16 v[4:7], v[234:237], v[202:205], v[230:233]
	v_mfma_f32_16x16x32_bf16 v[24:27], v[238:241], v[206:209], v[4:7]
	v_mfma_f32_16x16x32_bf16 v[4:7], v[242:245], v[202:205], v[166:169]
	v_mfma_f32_16x16x32_bf16 v[20:23], v[246:249], v[206:209], v[4:7]
	v_mfma_f32_16x16x32_bf16 v[4:7], v[234:237], v[210:213], v[170:173]
	v_mfma_f32_16x16x32_bf16 v[8:11], v[238:241], v[40:43], v[4:7]
	v_mfma_f32_16x16x32_bf16 v[4:7], v[242:245], v[210:213], v[178:181]
	v_mfma_f32_16x16x32_bf16 v[4:7], v[246:249], v[40:43], v[4:7]
	s_setprio 0
	s_lshl_b32 s6, s6, 8
	s_barrier
	v_mbcnt_lo_u32_b32 v40, -1, 0
	v_mbcnt_hi_u32_b32 v40, -1, v40
	s_add_i32 s6, s6, s22
	v_and_or_b32 v152, v40, 15, s6
	s_lshl_b32 s6, s7, 8
	v_ashrrev_i32_e32 v40, 1, v40
	s_or_b32 s6, s6, s23
	v_and_b32_e32 v40, -8, v40
	v_add_u32_e32 v144, s6, v40
	v_or_b32_e32 v132, 4, v144
	v_or_b32_e32 v136, 1, v144
	v_ashrrev_i32_e32 v145, 31, v144
	v_readlane_b32 s28, v253, 12
	v_ashrrev_i32_e32 v133, 31, v132
	v_ashrrev_i32_e32 v137, 31, v136
	v_lshlrev_b64 v[40:41], 6, v[144:145]
	v_readlane_b32 s29, v253, 13
	v_lshlrev_b64 v[132:133], 6, v[132:133]
	v_lshlrev_b64 v[136:137], 6, v[136:137]
	v_lshl_add_u64 v[146:147], s[28:29], 0, v[40:41]
	v_lshl_add_u64 v[132:133], s[28:29], 0, v[132:133]
	v_lshl_add_u64 v[136:137], s[28:29], 0, v[136:137]
	global_load_dwordx4 v[178:181], v[146:147], off offset:32
	global_load_dwordx4 v[182:185], v[146:147], off offset:96
	global_load_dwordx4 v[186:189], v[146:147], off offset:160
	global_load_dwordx4 v[190:193], v[146:147], off offset:224
	global_load_dwordx4 v[194:197], v[146:147], off offset:288
	global_load_dwordx4 v[198:201], v[146:147], off offset:352
	global_load_dwordx4 v[202:205], v[146:147], off offset:416
	global_load_dwordx4 v[206:209], v[146:147], off offset:480
	v_add_co_u32_e32 v212, vcc, 0x2000, v146
	v_addc_co_u32_e32 v213, vcc, 0, v147, vcc
	global_load_dwordx4 v[218:221], v[212:213], off offset:32
	global_load_dwordx4 v[222:225], v[212:213], off offset:96
	global_load_dwordx4 v[226:229], v[212:213], off offset:160
	global_load_dwordx4 v[230:233], v[212:213], off offset:224
	global_load_dwordx4 v[234:237], v[212:213], off offset:288
	global_load_dwordx4 v[238:241], v[212:213], off offset:352
	global_load_dwordx4 v[242:245], v[212:213], off offset:416
	global_load_dwordx4 v[246:249], v[212:213], off offset:480
	s_waitcnt vmcnt(0)
; __device__ __forceinline__ u32x4 pack8(f32x4 a, f32x4 b) { u32x4 r; r[0] = cvt_pk_bf16(a[0], a[1]); r[1] = cvt_pk_bf16(a[2], a[3]); r[2] = cvt_pk_bf16(b[0], b[1]); r[3] = cvt_pk_bf16(b[2], b[3]); return r; }
;     __device__ __forceinline__ void operator()(const AccT& acc, const Unit& u, int wr, int wc, int fr, int fq) const {
;     ...
;             for (int j = 0; j < 4; ++j) { const f32x4 pc = *(const f32x4*)(ssp + (size_t)(col + j) * 16 + 8), pd = *(const f32x4*)(ssp + (size_t)(col + 4 + j) * 16 + 8);
;                 s0[j] = rsqrtf(((pc[0] + pc[1]) + (pc[2] + pc[3])) * (1.0f / 256.0f) + EPS); s1[j] = rsqrtf(((pd[0] + pd[1]) + (pd[2] + pd[3])) * (1.0f / 256.0f) + EPS); }
; #pragma unroll
;             for (int ai = 0; ai < 2; ++ai)
; #pragma unroll
;                 for (int m = 0; m < 4; ++m) {
;                     const int row = row0 + ai * HALF + m * 16;
;                     *(u32x4*)(Vt + (size_t)row * SEQ + col) = pack8(acc[ai][bj][m][0] * s0, acc[ai][bj][m][1] * s1);
	v_mov_b32_e32 v40, v178
	v_mov_b32_e32 v41, v179
	v_mov_b32_e32 v42, v180
	v_mov_b32_e32 v43, v181
	v_or_b32_e32 v142, 5, v144
	v_mov_b32_e32 v132, v194
	v_mov_b32_e32 v133, v195
	v_mov_b32_e32 v134, v196
	v_mov_b32_e32 v135, v197
	v_ashrrev_i32_e32 v143, 31, v142
	v_mov_b32_e32 v136, v182
	v_mov_b32_e32 v137, v183
	v_mov_b32_e32 v138, v184
	v_mov_b32_e32 v139, v185
	v_lshlrev_b64 v[142:143], 6, v[142:143]
	v_lshl_add_u64 v[142:143], s[28:29], 0, v[142:143]
	v_mov_b32_e32 v162, v198
	v_mov_b32_e32 v163, v199
	v_mov_b32_e32 v164, v200
	v_mov_b32_e32 v165, v201
	s_mov_b32 s6, 0x358637bd
	s_mov_b32 s52, 0x3b800000
	s_mov_b32 s11, 0x800000
	s_mov_b32 s30, 0x45800000
	v_ashrrev_i32_e32 v153, 31, v152
	v_readlane_b32 s56, v254, 48
	v_readlane_b32 s58, v253, 14
	s_mov_b32 s92, 0x800000
	s_add_i32 s26, s26, s53
	s_mov_b64 s[90:91], s[68:69]
	s_mov_b64 s[86:87], s[62:63]
	v_readlane_b32 s57, v254, 49
	v_readlane_b32 s59, v253, 15
	v_mov_b32_e32 v142, v40
	v_mov_b32_e32 v143, v136
	v_mov_b32_e32 v136, v41
	v_pk_add_f32 v[40:41], v[142:143], v[136:137]
	v_mov_b32_e32 v136, v42
	v_mov_b32_e32 v137, v138
	v_mov_b32_e32 v138, v43
	v_pk_add_f32 v[42:43], v[136:137], v[138:139]
	v_mov_b64_e32 v[142:143], s[6:7]
	v_pk_add_f32 v[40:41], v[40:41], v[42:43]
	v_or_b32_e32 v136, 3, v144
	v_pk_fma_f32 v[40:41], v[40:41], s[52:53], v[142:143] op_sel_hi:[1,0,0]
	v_ashrrev_i32_e32 v137, 31, v136
	v_mul_f32_e32 v42, 0x4b800000, v40
	v_cmp_gt_f32_e64 s[6:7], s11, v40
	v_cmp_gt_f32_e32 vcc, s11, v41
	v_lshlrev_b64 v[136:137], 6, v[136:137]
	v_cndmask_b32_e64 v40, v40, v42, s[6:7]
	v_mul_f32_e32 v42, 0x4b800000, v41
	v_cndmask_b32_e32 v41, v41, v42, vcc
	v_rsq_f32_e32 v40, v40
	v_rsq_f32_e32 v41, v41
	v_lshl_add_u64 v[136:137], s[28:29], 0, v[136:137]
	v_pk_mul_f32 v[42:43], v[40:41], s[30:31] op_sel_hi:[1,0]
	s_nop 0
	v_cndmask_b32_e32 v149, v41, v43, vcc
	v_cndmask_b32_e64 v148, v40, v42, s[6:7]
	v_mov_b32_e32 v40, v132
	v_mov_b32_e32 v41, v162
	v_mov_b32_e32 v162, v133
	v_mov_b32_e32 v42, v134
	v_mov_b32_e32 v43, v164
	v_mov_b32_e32 v164, v135
	v_pk_add_f32 v[40:41], v[40:41], v[162:163]
	v_pk_add_f32 v[42:43], v[42:43], v[164:165]
	v_mov_b32_e32 v162, v190
	v_mov_b32_e32 v163, v191
	v_mov_b32_e32 v164, v192
	v_mov_b32_e32 v165, v193
	v_pk_add_f32 v[40:41], v[40:41], v[42:43]
	v_or_b32_e32 v132, 6, v144
	v_pk_fma_f32 v[40:41], v[40:41], s[52:53], v[142:143] op_sel_hi:[1,0,0]
	v_or_b32_e32 v136, 7, v144
	v_mul_f32_e32 v42, 0x4b800000, v40
	v_cmp_gt_f32_e64 s[6:7], s11, v40
	v_cmp_gt_f32_e32 vcc, s11, v41
	v_ashrrev_i32_e32 v133, 31, v132
	v_cndmask_b32_e64 v40, v40, v42, s[6:7]
	v_mul_f32_e32 v42, 0x4b800000, v41
	v_cndmask_b32_e32 v41, v41, v42, vcc
	v_rsq_f32_e32 v40, v40
	v_rsq_f32_e32 v41, v41
	v_ashrrev_i32_e32 v137, 31, v136
	v_lshlrev_b64 v[132:133], 6, v[132:133]
	v_lshlrev_b64 v[136:137], 6, v[136:137]
	v_pk_mul_f32 v[42:43], v[40:41], s[30:31] op_sel_hi:[1,0]
	v_lshl_add_u64 v[132:133], s[28:29], 0, v[132:133]
	v_cndmask_b32_e64 v150, v40, v42, s[6:7]
	v_or_b32_e32 v40, 2, v144
	v_cndmask_b32_e32 v151, v41, v43, vcc
	v_ashrrev_i32_e32 v41, 31, v40
	v_lshlrev_b64 v[40:41], 6, v[40:41]
	v_lshl_add_u64 v[40:41], s[28:29], 0, v[40:41]
	v_mov_b32_e32 v40, v186
	v_mov_b32_e32 v41, v187
	v_mov_b32_e32 v42, v188
	v_mov_b32_e32 v43, v189
	v_lshl_add_u64 v[136:137], s[28:29], 0, v[136:137]
	v_mov_b32_e32 v132, v202
	v_mov_b32_e32 v133, v203
	v_mov_b32_e32 v134, v204
	v_mov_b32_e32 v135, v205
	v_pk_mul_f32 v[124:125], v[124:125], v[150:151]
	v_mov_b32_e32 v136, v206
	v_mov_b32_e32 v137, v207
	v_mov_b32_e32 v138, v208
	v_mov_b32_e32 v139, v209
	v_pk_mul_f32 v[116:117], v[116:117], v[150:151]
	v_pk_mul_f32 v[100:101], v[100:101], v[150:151]
	v_pk_mul_f32 v[84:85], v[84:85], v[150:151]
	v_pk_mul_f32 v[76:77], v[76:77], v[150:151]
	v_pk_mul_f32 v[68:69], v[68:69], v[150:151]
	v_mov_b32_e32 v155, v162
	v_mov_b32_e32 v154, v40
	v_mov_b32_e32 v162, v41
	v_pk_add_f32 v[40:41], v[154:155], v[162:163]
	v_mov_b32_e32 v154, v42
	v_mov_b32_e32 v155, v164
	v_mov_b32_e32 v164, v43
	v_pk_add_f32 v[42:43], v[154:155], v[164:165]
	s_nop 0
	v_pk_add_f32 v[40:41], v[40:41], v[42:43]
	s_nop 0
	v_pk_fma_f32 v[40:41], v[40:41], s[52:53], v[142:143] op_sel_hi:[1,0,0]
	s_nop 0
	v_mul_f32_e32 v42, 0x4b800000, v40
	v_cmp_gt_f32_e64 s[6:7], s11, v40
	v_cmp_gt_f32_e32 vcc, s11, v41
	s_nop 0
	v_cndmask_b32_e64 v40, v40, v42, s[6:7]
	v_mul_f32_e32 v42, 0x4b800000, v41
	v_cndmask_b32_e32 v41, v41, v42, vcc
	v_rsq_f32_e32 v40, v40
	v_rsq_f32_e32 v41, v41
	s_nop 0
	v_pk_mul_f32 v[42:43], v[40:41], s[30:31] op_sel_hi:[1,0]
	s_nop 0
	v_cndmask_b32_e32 v155, v41, v43, vcc
	v_cndmask_b32_e64 v154, v40, v42, s[6:7]
	v_mov_b32_e32 v40, v132
	v_mov_b32_e32 v41, v136
	v_mov_b32_e32 v136, v133
	v_mov_b32_e32 v42, v134
	v_mov_b32_e32 v43, v138
	v_mov_b32_e32 v138, v135
	v_pk_add_f32 v[40:41], v[40:41], v[136:137]
	v_pk_add_f32 v[42:43], v[42:43], v[138:139]
	s_nop 0
	v_pk_add_f32 v[40:41], v[40:41], v[42:43]
	s_nop 0
	v_pk_fma_f32 v[40:41], v[40:41], s[52:53], v[142:143] op_sel_hi:[1,0,0]
	s_nop 0
	v_mul_f32_e32 v42, 0x4b800000, v40
	v_cmp_gt_f32_e64 s[6:7], s11, v40
	v_cmp_gt_f32_e32 vcc, s11, v41
	s_nop 0
	v_cndmask_b32_e64 v40, v40, v42, s[6:7]
	v_mul_f32_e32 v42, 0x4b800000, v41
	v_cndmask_b32_e32 v41, v41, v42, vcc
	v_rsq_f32_e32 v40, v40
	v_rsq_f32_e32 v41, v41
	s_nop 0
	v_pk_mul_f32 v[42:43], v[40:41], s[30:31] op_sel_hi:[1,0]
	s_nop 0
	v_cndmask_b32_e32 v133, v41, v43, vcc
	v_cndmask_b32_e64 v132, v40, v42, s[6:7]
	v_pk_mul_f32 v[42:43], v[130:131], v[154:155]
	v_pk_mul_f32 v[40:41], v[128:129], v[148:149]
	v_readlane_b32 s6, v253, 8
	v_pk_mul_f32 v[126:127], v[126:127], v[132:133]
; __device__ __forceinline__ u32x4 pack8(f32x4 a, f32x4 b) { u32x4 r; r[0] = cvt_pk_bf16(a[0], a[1]); r[1] = cvt_pk_bf16(a[2], a[3]); r[2] = cvt_pk_bf16(b[0], b[1]); r[3] = cvt_pk_bf16(b[2], b[3]); return r; }
;     __device__ __forceinline__ void operator()(const AccT& acc, const Unit& u, int wr, int wc, int fr, int fq) const {
;     ...
;             for (int j = 0; j < 4; ++j) { const f32x4 pc = *(const f32x4*)(ssp + (size_t)(col + j) * 16 + 8), pd = *(const f32x4*)(ssp + (size_t)(col + 4 + j) * 16 + 8);
;                 s0[j] = rsqrtf(((pc[0] + pc[1]) + (pc[2] + pc[3])) * (1.0f / 256.0f) + EPS); s1[j] = rsqrtf(((pd[0] + pd[1]) + (pd[2] + pd[3])) * (1.0f / 256.0f) + EPS); }
; #pragma unroll
;             for (int ai = 0; ai < 2; ++ai)
; #pragma unroll
;                 for (int m = 0; m < 4; ++m) {
;                     const int row = row0 + ai * HALF + m * 16;
;                     *(u32x4*)(Vt + (size_t)row * SEQ + col) = pack8(acc[ai][bj][m][0] * s0, acc[ai][bj][m][1] * s1);
	v_cvt_pk_bf16_f32 v40, v40, v41
	v_cvt_pk_bf16_f32 v41, v42, v43
	v_cvt_pk_bf16_f32 v42, v124, v125
	v_lshlrev_b64 v[124:125], 15, v[152:153]
	v_readlane_b32 s7, v253, 9
	v_cvt_pk_bf16_f32 v43, v126, v127
	v_lshlrev_b64 v[126:127], 1, v[144:145]
	v_or_b32_e32 v128, 16, v152
	v_lshl_add_u64 v[124:125], s[6:7], 0, v[124:125]
	v_lshl_add_u64 v[124:125], v[124:125], 0, v[126:127]
	global_store_dwordx4 v[124:125], v[40:43], off
	v_ashrrev_i32_e32 v129, 31, v128
	v_pk_mul_f32 v[118:119], v[118:119], v[132:133]
	v_pk_mul_f32 v[42:43], v[122:123], v[154:155]
	v_pk_mul_f32 v[40:41], v[120:121], v[148:149]
	v_pk_mul_f32 v[102:103], v[102:103], v[132:133]
	v_cvt_pk_bf16_f32 v40, v40, v41
	v_cvt_pk_bf16_f32 v41, v42, v43
	v_cvt_pk_bf16_f32 v42, v116, v117
	v_lshlrev_b64 v[116:117], 15, v[128:129]
	v_lshl_add_u64 v[116:117], s[6:7], 0, v[116:117]
	v_cvt_pk_bf16_f32 v43, v118, v119
	v_lshl_add_u64 v[116:117], v[116:117], 0, v[126:127]
	v_or_b32_e32 v118, 32, v152
	global_store_dwordx4 v[116:117], v[40:43], off
	v_ashrrev_i32_e32 v119, 31, v118
	v_pk_mul_f32 v[86:87], v[86:87], v[132:133]
	v_pk_mul_f32 v[42:43], v[106:107], v[154:155]
	v_pk_mul_f32 v[40:41], v[104:105], v[148:149]
	v_pk_mul_f32 v[78:79], v[78:79], v[132:133]
	v_cvt_pk_bf16_f32 v40, v40, v41
	v_cvt_pk_bf16_f32 v41, v42, v43
	v_cvt_pk_bf16_f32 v42, v100, v101
	v_lshlrev_b64 v[100:101], 15, v[118:119]
	v_lshl_add_u64 v[100:101], s[6:7], 0, v[100:101]
	v_cvt_pk_bf16_f32 v43, v102, v103
	v_lshl_add_u64 v[100:101], v[100:101], 0, v[126:127]
	v_or_b32_e32 v102, 48, v152
	global_store_dwordx4 v[100:101], v[40:43], off
	v_ashrrev_i32_e32 v103, 31, v102
	v_pk_mul_f32 v[70:71], v[70:71], v[132:133]
	v_pk_mul_f32 v[42:43], v[90:91], v[154:155]
	v_pk_mul_f32 v[40:41], v[88:89], v[148:149]
	v_pk_mul_f32 v[88:89], v[108:109], v[150:151]
	v_cvt_pk_bf16_f32 v40, v40, v41
	v_cvt_pk_bf16_f32 v41, v42, v43
	v_cvt_pk_bf16_f32 v42, v84, v85
	v_lshlrev_b64 v[84:85], 15, v[102:103]
	v_lshl_add_u64 v[84:85], s[6:7], 0, v[84:85]
	v_cvt_pk_bf16_f32 v43, v86, v87
	v_lshl_add_u64 v[86:87], v[84:85], 0, v[126:127]
	global_store_dwordx4 v[86:87], v[40:43], off
	v_pk_mul_f32 v[84:85], v[110:111], v[132:133]
	s_mov_b64 s[6:7], 0x400000
	v_pk_mul_f32 v[42:43], v[114:115], v[154:155]
	v_pk_mul_f32 v[40:41], v[112:113], v[148:149]
	v_pk_mul_f32 v[90:91], v[92:93], v[150:151]
	v_cvt_pk_bf16_f32 v40, v40, v41
	v_cvt_pk_bf16_f32 v41, v42, v43
	v_cvt_pk_bf16_f32 v42, v88, v89
	v_cvt_pk_bf16_f32 v43, v84, v85
	v_lshl_add_u64 v[84:85], v[124:125], 0, s[6:7]
	s_mov_b32 s6, 0x400000
	v_add_co_u32_e32 v88, vcc, s6, v124
	s_mov_b64 s[6:7], 0x480000
	s_nop 0
	v_addc_co_u32_e32 v89, vcc, 0, v125, vcc
	global_store_dwordx4 v[88:89], v[40:43], off
	v_pk_mul_f32 v[88:89], v[94:95], v[132:133]
	s_nop 0
	v_pk_mul_f32 v[42:43], v[98:99], v[154:155]
	v_pk_mul_f32 v[40:41], v[96:97], v[148:149]
	s_nop 0
	v_cvt_pk_bf16_f32 v40, v40, v41
	v_cvt_pk_bf16_f32 v41, v42, v43
	v_cvt_pk_bf16_f32 v42, v90, v91
	v_cvt_pk_bf16_f32 v43, v88, v89
	v_lshl_add_u64 v[88:89], v[124:125], 0, s[6:7]
	s_mov_b32 s6, 0x480000
	v_add_co_u32_e32 v90, vcc, s6, v124
	s_mov_b64 s[6:7], 0x500000
	s_nop 0
	v_addc_co_u32_e32 v91, vcc, 0, v125, vcc
	global_store_dwordx4 v[90:91], v[40:43], off
	s_nop 1
	v_pk_mul_f32 v[42:43], v[82:83], v[154:155]
	v_pk_mul_f32 v[40:41], v[80:81], v[148:149]
	v_add_u32_e32 v80, 0x85, v144
	v_cvt_pk_bf16_f32 v40, v40, v41
	v_cvt_pk_bf16_f32 v41, v42, v43
	v_cvt_pk_bf16_f32 v42, v76, v77
	v_lshl_add_u64 v[76:77], v[124:125], 0, s[6:7]
	s_mov_b32 s6, 0x500000
	v_cvt_pk_bf16_f32 v43, v78, v79
	v_add_co_u32_e32 v78, vcc, s6, v124
	s_mov_b64 s[6:7], 0x580000
	s_nop 0
	v_addc_co_u32_e32 v79, vcc, 0, v125, vcc
	global_store_dwordx4 v[78:79], v[40:43], off
	v_lshl_add_u64 v[78:79], v[124:125], 0, s[6:7]
	s_mov_b32 s6, 0x580000
	v_pk_mul_f32 v[42:43], v[74:75], v[154:155]
	v_pk_mul_f32 v[40:41], v[72:73], v[148:149]
	v_add_u32_e32 v72, 0x81, v144
	v_cvt_pk_bf16_f32 v40, v40, v41
	v_cvt_pk_bf16_f32 v41, v42, v43
	v_cvt_pk_bf16_f32 v42, v68, v69
	v_add_co_u32_e32 v68, vcc, s6, v124
	s_movk_i32 s6, 0x2000
	s_nop 0
	v_addc_co_u32_e32 v69, vcc, 0, v125, vcc
	v_ashrrev_i32_e32 v73, 31, v72
	v_cvt_pk_bf16_f32 v43, v70, v71
	global_store_dwordx4 v[68:69], v[40:43], off
	v_lshlrev_b64 v[72:73], 6, v[72:73]
	v_lshl_add_u64 v[72:73], s[28:29], 0, v[72:73]
	v_add_co_u32_e32 v40, vcc, s6, v146
	v_mov_b32_e32 v72, v222
	v_mov_b32_e32 v73, v223
	v_mov_b32_e32 v74, v224
	v_mov_b32_e32 v75, v225
	s_nop 0
	v_addc_co_u32_e32 v41, vcc, 0, v147, vcc
	v_mov_b32_e32 v40, v218
	v_mov_b32_e32 v41, v219
	v_mov_b32_e32 v42, v220
	v_mov_b32_e32 v43, v221
	v_add_u32_e32 v68, 0x84, v144
	v_ashrrev_i32_e32 v69, 31, v68
	v_ashrrev_i32_e32 v81, 31, v80
	v_lshlrev_b64 v[68:69], 6, v[68:69]
	v_lshlrev_b64 v[80:81], 6, v[80:81]
	v_lshl_add_u64 v[68:69], s[28:29], 0, v[68:69]
	v_lshl_add_u64 v[80:81], s[28:29], 0, v[80:81]
	v_mov_b32_e32 v68, v234
	v_mov_b32_e32 v69, v235
	v_mov_b32_e32 v70, v236
	v_mov_b32_e32 v71, v237
	s_nop 0
	v_mov_b32_e32 v90, v238
	v_mov_b32_e32 v91, v239
	v_mov_b32_e32 v92, v240
	v_mov_b32_e32 v93, v241
	v_mov_b32_e32 v81, v72
	v_mov_b32_e32 v80, v40
	v_mov_b32_e32 v72, v41
	v_pk_add_f32 v[40:41], v[80:81], v[72:73]
	v_mov_b32_e32 v72, v42
	v_mov_b32_e32 v73, v74
	v_mov_b32_e32 v74, v43
	v_pk_add_f32 v[42:43], v[72:73], v[74:75]
	s_nop 0
	v_pk_add_f32 v[40:41], v[40:41], v[42:43]
	s_nop 0
	v_pk_fma_f32 v[40:41], v[40:41], s[52:53], v[142:143] op_sel_hi:[1,0,0]
	s_nop 0
	v_mul_f32_e32 v42, 0x4b800000, v40
	v_cmp_gt_f32_e64 s[6:7], s11, v40
	v_cmp_gt_f32_e32 vcc, s11, v41
	s_nop 0
	v_cndmask_b32_e64 v40, v40, v42, s[6:7]
	v_mul_f32_e32 v42, 0x4b800000, v41
; __device__ __forceinline__ u32x4 pack8(f32x4 a, f32x4 b) { u32x4 r; r[0] = cvt_pk_bf16(a[0], a[1]); r[1] = cvt_pk_bf16(a[2], a[3]); r[2] = cvt_pk_bf16(b[0], b[1]); r[3] = cvt_pk_bf16(b[2], b[3]); return r; }
;     __device__ __forceinline__ void operator()(const AccT& acc, const Unit& u, int wr, int wc, int fr, int fq) const {
;     ...
;             for (int j = 0; j < 4; ++j) { const f32x4 pc = *(const f32x4*)(ssp + (size_t)(col + j) * 16 + 8), pd = *(const f32x4*)(ssp + (size_t)(col + 4 + j) * 16 + 8);
;                 s0[j] = rsqrtf(((pc[0] + pc[1]) + (pc[2] + pc[3])) * (1.0f / 256.0f) + EPS); s1[j] = rsqrtf(((pd[0] + pd[1]) + (pd[2] + pd[3])) * (1.0f / 256.0f) + EPS); }
; #pragma unroll
;             for (int ai = 0; ai < 2; ++ai)
; #pragma unroll
;                 for (int m = 0; m < 4; ++m) {
;                     const int row = row0 + ai * HALF + m * 16;
;                     *(u32x4*)(Vt + (size_t)row * SEQ + col) = pack8(acc[ai][bj][m][0] * s0, acc[ai][bj][m][1] * s1);
;                 }
	v_cndmask_b32_e32 v41, v41, v42, vcc
	v_rsq_f32_e32 v40, v40
	v_rsq_f32_e32 v41, v41
	s_nop 0
	v_pk_mul_f32 v[42:43], v[40:41], s[30:31] op_sel_hi:[1,0]
	s_nop 0
	v_cndmask_b32_e32 v81, v41, v43, vcc
	v_cndmask_b32_e64 v80, v40, v42, s[6:7]
	v_mov_b32_e32 v40, v68
	v_mov_b32_e32 v41, v90
	v_mov_b32_e32 v90, v69
	v_mov_b32_e32 v42, v70
	v_mov_b32_e32 v43, v92
	v_mov_b32_e32 v92, v71
	v_pk_add_f32 v[40:41], v[40:41], v[90:91]
	v_pk_add_f32 v[42:43], v[42:43], v[92:93]
	v_add_u32_e32 v90, 0x87, v144
	v_pk_add_f32 v[40:41], v[40:41], v[42:43]
	v_ashrrev_i32_e32 v91, 31, v90
	v_pk_fma_f32 v[40:41], v[40:41], s[52:53], v[142:143] op_sel_hi:[1,0,0]
	v_lshlrev_b64 v[90:91], 6, v[90:91]
	v_mul_f32_e32 v42, 0x4b800000, v40
	v_cmp_gt_f32_e64 s[6:7], s11, v40
	v_cmp_gt_f32_e32 vcc, s11, v41
	v_lshl_add_u64 v[90:91], s[28:29], 0, v[90:91]
	v_cndmask_b32_e64 v40, v40, v42, s[6:7]
	v_mul_f32_e32 v42, 0x4b800000, v41
	v_cndmask_b32_e32 v41, v41, v42, vcc
	v_rsq_f32_e32 v40, v40
	v_rsq_f32_e32 v41, v41
	v_mov_b32_e32 v90, v246
	v_mov_b32_e32 v91, v247
	v_mov_b32_e32 v92, v248
	v_mov_b32_e32 v93, v249
	v_pk_mul_f32 v[32:33], v[32:33], v[80:81]
	v_pk_mul_f32 v[16:17], v[16:17], v[80:81]
	v_pk_mul_f32 v[42:43], v[40:41], s[30:31] op_sel_hi:[1,0]
	v_pk_mul_f32 v[8:9], v[8:9], v[80:81]
	v_cndmask_b32_e64 v82, v40, v42, s[6:7]
	v_add_u32_e32 v40, 0x82, v144
	v_cndmask_b32_e32 v83, v41, v43, vcc
	v_ashrrev_i32_e32 v41, 31, v40
	v_lshlrev_b64 v[40:41], 6, v[40:41]
	v_lshl_add_u64 v[40:41], s[28:29], 0, v[40:41]
	v_mov_b32_e32 v72, v226
	v_mov_b32_e32 v73, v227
	v_mov_b32_e32 v74, v228
	v_mov_b32_e32 v75, v229
	v_add_u32_e32 v40, 0x86, v144
	v_ashrrev_i32_e32 v41, 31, v40
	v_lshlrev_b64 v[40:41], 6, v[40:41]
	v_lshl_add_u64 v[40:41], s[28:29], 0, v[40:41]
	v_mov_b32_e32 v68, v242
	v_mov_b32_e32 v69, v243
	v_mov_b32_e32 v70, v244
	v_mov_b32_e32 v71, v245
	v_add_u32_e32 v40, 0x83, v144
	v_ashrrev_i32_e32 v41, 31, v40
	v_lshlrev_b64 v[40:41], 6, v[40:41]
	v_lshl_add_u64 v[40:41], s[28:29], 0, v[40:41]
	v_mov_b32_e32 v40, v230
	v_mov_b32_e32 v41, v231
	v_mov_b32_e32 v42, v232
	v_mov_b32_e32 v43, v233
	v_pk_mul_f32 v[60:61], v[60:61], v[82:83]
	v_pk_mul_f32 v[44:45], v[44:45], v[82:83]
	v_readlane_b32 s28, v254, 44
	v_readlane_b32 s29, v254, 45
	v_mov_b32_e32 v94, v72
	v_mov_b32_e32 v72, v74
	v_mov_b32_e32 v95, v40
	v_mov_b32_e32 v40, v73
	v_mov_b32_e32 v73, v42
	v_mov_b32_e32 v42, v75
	v_pk_add_f32 v[40:41], v[94:95], v[40:41]
	v_pk_add_f32 v[42:43], v[72:73], v[42:43]
	s_nop 0
	v_pk_add_f32 v[40:41], v[40:41], v[42:43]
	s_nop 0
	v_pk_fma_f32 v[40:41], v[40:41], s[52:53], v[142:143] op_sel_hi:[1,0,0]
	s_nop 0
	v_mul_f32_e32 v42, 0x4b800000, v40
	v_cmp_gt_f32_e64 s[6:7], s11, v40
	v_cmp_gt_f32_e32 vcc, s11, v41
	s_nop 0
	v_cndmask_b32_e64 v40, v40, v42, s[6:7]
	v_mul_f32_e32 v42, 0x4b800000, v41
	v_cndmask_b32_e32 v41, v41, v42, vcc
	v_rsq_f32_e32 v40, v40
	v_rsq_f32_e32 v41, v41
	s_nop 0
	v_pk_mul_f32 v[42:43], v[40:41], s[30:31] op_sel_hi:[1,0]
	s_nop 0
	v_cndmask_b32_e32 v73, v41, v43, vcc
	v_cndmask_b32_e64 v72, v40, v42, s[6:7]
	v_mov_b32_e32 v40, v68
	v_mov_b32_e32 v41, v90
	v_mov_b32_e32 v90, v69
	v_mov_b32_e32 v42, v70
	v_mov_b32_e32 v43, v92
	v_mov_b32_e32 v92, v71
	v_pk_add_f32 v[40:41], v[40:41], v[90:91]
	v_pk_add_f32 v[42:43], v[42:43], v[92:93]
	v_pk_mul_f32 v[34:35], v[34:35], v[72:73]
	v_pk_add_f32 v[40:41], v[40:41], v[42:43]
	v_pk_mul_f32 v[18:19], v[18:19], v[72:73]
	v_pk_fma_f32 v[40:41], v[40:41], s[52:53], v[142:143] op_sel_hi:[1,0,0]
	v_pk_mul_f32 v[10:11], v[10:11], v[72:73]
	v_mul_f32_e32 v42, 0x4b800000, v40
	v_cmp_gt_f32_e64 s[6:7], s11, v40
	v_cmp_gt_f32_e32 vcc, s11, v41
	s_nop 0
	v_cndmask_b32_e64 v40, v40, v42, s[6:7]
	v_mul_f32_e32 v42, 0x4b800000, v41
	v_cndmask_b32_e32 v41, v41, v42, vcc
	v_rsq_f32_e32 v40, v40
	v_rsq_f32_e32 v41, v41
	s_nop 0
	v_pk_mul_f32 v[42:43], v[40:41], s[30:31] op_sel_hi:[1,0]
	s_nop 0
	v_cndmask_b32_e32 v69, v41, v43, vcc
	v_cndmask_b32_e64 v68, v40, v42, s[6:7]
	v_pk_mul_f32 v[40:41], v[64:65], v[80:81]
	v_pk_mul_f32 v[42:43], v[66:67], v[72:73]
	v_cvt_pk_bf16_f32 v40, v40, v41
	v_pk_mul_f32 v[62:63], v[62:63], v[68:69]
	v_cvt_pk_bf16_f32 v41, v42, v43
	v_cvt_pk_bf16_f32 v42, v60, v61
	v_pk_mul_f32 v[46:47], v[46:47], v[68:69]
	v_cvt_pk_bf16_f32 v43, v62, v63
	global_store_dwordx4 v[124:125], v[40:43], off offset:256
	v_readlane_b32 s30, v254, 42
	s_andn2_b64 vcc, exec, s[4:5]
	v_pk_mul_f32 v[40:41], v[48:49], v[80:81]
	v_pk_mul_f32 v[42:43], v[50:51], v[72:73]
	v_cvt_pk_bf16_f32 v40, v40, v41
	s_mov_b32 s7, s10
	v_cvt_pk_bf16_f32 v41, v42, v43
	v_cvt_pk_bf16_f32 v42, v44, v45
	v_cvt_pk_bf16_f32 v43, v46, v47
	global_store_dwordx4 v[116:117], v[40:43], off offset:256
	s_mov_b32 s6, s12
	v_readlane_b32 s31, v254, 43
	v_pk_mul_f32 v[40:41], v[30:31], v[68:69]
	v_pk_mul_f32 v[30:31], v[28:29], v[82:83]
	v_cvt_pk_bf16_f32 v28, v32, v33
	v_cvt_pk_bf16_f32 v29, v34, v35
	v_readlane_b32 s4, v254, 46
	v_cvt_pk_bf16_f32 v30, v30, v31
	v_cvt_pk_bf16_f32 v31, v40, v41
	global_store_dwordx4 v[100:101], v[28:31], off offset:256
	v_readlane_b32 s5, v254, 47
	s_nop 0
	v_pk_mul_f32 v[28:29], v[14:15], v[68:69]
	v_pk_mul_f32 v[14:15], v[12:13], v[82:83]
	v_cvt_pk_bf16_f32 v12, v16, v17
	v_cvt_pk_bf16_f32 v13, v18, v19
	v_pk_mul_f32 v[16:17], v[54:55], v[68:69]
	v_cvt_pk_bf16_f32 v14, v14, v15
	v_cvt_pk_bf16_f32 v15, v28, v29
	global_store_dwordx4 v[86:87], v[12:15], off offset:256
	v_pk_mul_f32 v[18:19], v[52:53], v[82:83]
	s_nop 0
	v_pk_mul_f32 v[12:13], v[56:57], v[80:81]
	v_pk_mul_f32 v[14:15], v[58:59], v[72:73]
	v_cvt_pk_bf16_f32 v12, v12, v13
	s_nop 0
	v_cvt_pk_bf16_f32 v13, v14, v15
	v_cvt_pk_bf16_f32 v14, v18, v19
	v_cvt_pk_bf16_f32 v15, v16, v17
	global_store_dwordx4 v[84:85], v[12:15], off offset:256
	v_pk_mul_f32 v[16:17], v[38:39], v[68:69]
	v_pk_mul_f32 v[18:19], v[36:37], v[82:83]
	v_pk_mul_f32 v[12:13], v[158:159], v[80:81]
	v_pk_mul_f32 v[14:15], v[160:161], v[72:73]
	v_cvt_pk_bf16_f32 v12, v12, v13
	s_nop 0
	v_cvt_pk_bf16_f32 v13, v14, v15
	v_cvt_pk_bf16_f32 v14, v18, v19
	v_cvt_pk_bf16_f32 v15, v16, v17
	global_store_dwordx4 v[88:89], v[12:15], off offset:256
	v_pk_mul_f32 v[16:17], v[22:23], v[68:69]
	v_pk_mul_f32 v[18:19], v[20:21], v[82:83]
	v_pk_mul_f32 v[12:13], v[24:25], v[80:81]
	v_pk_mul_f32 v[14:15], v[26:27], v[72:73]
	v_cvt_pk_bf16_f32 v12, v12, v13
	s_nop 0
	v_cvt_pk_bf16_f32 v13, v14, v15
	v_cvt_pk_bf16_f32 v14, v18, v19
	v_cvt_pk_bf16_f32 v15, v16, v17
	global_store_dwordx4 v[76:77], v[12:15], off offset:256
	s_nop 1
	v_pk_mul_f32 v[12:13], v[6:7], v[68:69]
	v_pk_mul_f32 v[6:7], v[4:5], v[82:83]
	v_cvt_pk_bf16_f32 v4, v8, v9
	v_cvt_pk_bf16_f32 v5, v10, v11
	s_nop 0
	v_cvt_pk_bf16_f32 v6, v6, v7
	v_cvt_pk_bf16_f32 v7, v12, v13
	global_store_dwordx4 v[78:79], v[4:7], off offset:256
	s_cbranch_vccz .LBB0_192
